# v031 + attention post-loop wait relaxed to lgkmcnt (touch completes in background) + queue code no longer drains stores per unit + cross prompt epilogue: results written in place into the LDS tile, 8
# baseline (speedup 1.0000x reference)
; DI int tid_now() { int t; asm volatile("v_mov_b32 %0, %1" : "=v"(t) : "v"((int)threadIdx.x)); return t; }
; #define Q_NEXT(k, id) do { if (tid == 0) qw[qit & 1] = __hip_atomic_fetch_add(qctr + 64 * (k), 1u, __ATOMIC_RELAXED, __HIP_MEMORY_SCOPE_AGENT); __syncthreads(); \
;         id = __builtin_amdgcn_readfirstlane((int)qw[qit & 1]); ++qit; } while (0)
; __global__ void __launch_bounds__(512, 2) fwd(Args args) {
;     ...
; #pragma unroll 1
;         for (;;) { int id; Q_NEXT(2, id); if (id >= 2048) break; const int lane = tid_now() & 63; fa::attn_unit(A_, lds, id >> 8, (id >> 5) & 7, 31 - (id & 31), lam, wave, lane); }
.LBB0_861:
	s_add_u32 s2, s50, 0x20200
	s_addc_u32 s3, s51, 0
	s_lshr_b32 s24, s63, 1
	s_add_u32 s25, s50, 0x70c00000
	s_addc_u32 s26, s51, 0
	s_lshl_b32 s0, s33, 1
	s_or_b32 s27, s0, 1
	s_and_b32 s4, s0, 2
	v_readlane_b32 s0, v255, 22
	s_ashr_i32 s5, s0, 7
	s_lshl_b32 s0, s5, 5
	s_lshl_b32 s12, s33, 4
	s_lshl_b32 s33, s33, 11
	s_lshl_b32 s16, s27, 3
	s_lshl_b32 s38, s27, 10
	s_ashr_i32 s1, s0, 31
	s_ashr_i32 s13, s12, 31
	s_add_i32 s37, s33, 0
	s_ashr_i32 s17, s16, 31
	s_add_i32 s39, s38, 0
	s_lshl_b64 s[0:1], s[0:1], 1
	s_add_u32 s0, s50, s0
	s_addc_u32 s1, s51, s1
	s_add_u32 s28, s0, 0x74c00000
	s_addc_u32 s29, s1, 0
	s_lshl_b32 s30, s5, 12
	s_lshl_b32 s31, s4, 4
	s_lshl_b32 s34, s4, 10
	s_or_b32 s4, s4, 1
	s_add_i32 s0, s30, 0
	s_lshl_b32 s43, s4, 10
	s_add_i32 s1, s0, s34
	s_lshl_b32 s42, s4, 4
	s_add_i32 s0, s0, s43
	s_mov_b64 s[4:5], s[48:49]
	s_add_i32 s44, s0, 0x4000
	s_mov_b64 s[6:7], s[50:51]
	s_add_i32 s48, s0, 0xc000
	s_lshl_b32 s41, s84, 13
	s_lshl_b32 s0, s63, 14
	s_add_i32 s35, s1, 0x4000
	s_add_i32 s45, s37, 0x8000
	s_add_i32 s46, s39, 0x8000
	s_add_i32 s47, s1, 0xc000
	s_add_i32 s40, s85, 0x20400
	s_add_i32 s49, s41, 0
	s_add_i32 s50, s0, 0
	s_add_u32 s51, s6, 0x64900000
	s_addc_u32 s52, s7, 0
	s_or_b32 s53, s31, 0x90
	s_or_b32 s54, s31, 0x80
	s_add_u32 s55, s6, 0x70c08000
	s_mov_b32 s15, 0
	s_addc_u32 s56, s7, 0
	v_mov_b32_e32 v195, 0
	s_movk_i32 s57, 0x5800
	s_mov_b64 s[18:19], 0x4000
	v_mov_b32_e32 v211, 0x3727c5ac
	s_mov_b32 s58, 0xf800000
	v_mov_b32_e32 v212, 0x260
	s_mov_b32 s59, 0x3f4ccccd
	s_mov_b64 s[20:21], 0x1800
	s_movk_i32 s60, 0x1000
	s_movk_i32 s61, 0x7fff
	s_movk_i32 s62, 0x1800
	v_mov_b32_e32 v213, 0x5800
	s_and_saveexec_b64 s[0:1], s[82:83]
	s_cbranch_execz .Lattn_q_pre
	s_waitcnt vmcnt(0)
	v_mov_b32_e32 v205, 1
	s_nop 0
	global_atomic_add v205, v195, v205, s[2:3] sc0
	s_waitcnt vmcnt(0)

; DI int tid_now() { int t; asm volatile("v_mov_b32 %0, %1" : "=v"(t) : "v"((int)threadIdx.x)); return t; }
; #define Q_NEXT(k, id) do { if (tid == 0) qw[qit & 1] = __hip_atomic_fetch_add(qctr + 64 * (k), 1u, __ATOMIC_RELAXED, __HIP_MEMORY_SCOPE_AGENT); __syncthreads(); \
;         id = __builtin_amdgcn_readfirstlane((int)qw[qit & 1]); ++qit; } while (0)
; __global__ void __launch_bounds__(512, 2) fwd(Args args) {
;     ...
; #pragma unroll 1
;         for (;;) { int id; Q_NEXT(2, id); if (id >= 2048) break; const int lane = tid_now() & 63; fa::attn_unit(A_, lds, id >> 8, (id >> 5) & 7, 31 - (id & 31), lam, wave, lane); }
.LBB0_864:
	s_and_b32 s8, s36, 1
	s_and_saveexec_b64 s[0:1], s[82:83]
	s_cbranch_execz .LBB0_868
	s_mov_b64 s[6:7], exec
	v_mbcnt_lo_u32_b32 v2, s6, 0
	v_mbcnt_hi_u32_b32 v2, s7, v2
	v_cmp_eq_u32_e32 vcc, 0, v2
	s_and_saveexec_b64 s[4:5], vcc
	s_cbranch_execz .LBB0_867
	v_mov_b32_e32 v3, v205
	v_mov_b32_e32 v205, 1
	s_nop 0
	global_atomic_add v205, v195, v205, s[2:3] sc0

; DI float bf2f(unsigned short u) { return __uint_as_float((unsigned)u << 16); }
; DI unsigned f2bf(float f) { unsigned u = __float_as_uint(f); return (u + 0x7fffu + ((u >> 16) & 1u)) >> 16; }
; DI int crow(int i, int hh) { return (i & 3) + 8 * (i >> 2) + 4 * hh; }
; DI void attn_unit(Ctx A_, LAS unsigned char* lds, int b, int h, int qb, float lam, int wave, int lane) {
;     ...
;         for (int nb = 0; nb < 4; ++nb) {
;             const float sn = SUB_NORM[nb * 32 + r_e];
; #pragma unroll
;             for (int i = 0; i < 16; ++i) {
;                 const size_t rw = (size_t)(rowq_e + crow(i, hh_e));
;                 Y_[rw * YLD + C_YA + h_e * 128 + nb * 32 + r_e] = (bf16)f2bf(o[nb][i] * ssq[i] * sn * bf2f(P[rw * PLD + C_ZA + h_e * 128 + nb * 32 + r_e]));
;             }
.LBB0_890:
	v_readfirstlane_b32 s98, v0
	s_cmpk_gt_u32 s98, 0xff
	s_cbranch_scc1 .Lattn_touch_skip
	s_or_b32 s98, s64, s0
	s_mul_hi_u32 s99, s98, 0x5800
	s_mul_i32 s98, s98, 0x5800
	v_readlane_b32 s100, v255, 9
	v_readlane_b32 s101, v255, 10
	v_and_b32_e32 v206, 63, v0
	v_lshrrev_b32_e32 v207, 1, v206
	s_add_u32 s98, s98, s100
	s_addc_u32 s99, s99, s101
	s_lshl_b32 s100, s63, 8
	s_addk_i32 s100, 0x1800
	s_add_u32 s98, s98, s100
	s_addc_u32 s99, s99, 0
	v_mul_u32_u24_e32 v207, 0x5800, v207
	v_and_b32_e32 v206, 1, v206
	v_lshl_or_b32 v206, v206, 7, v207
	s_nop 0
	global_load_dword v207, v206, s[98:99]

; DI int crow(int i, int hh) { return (i & 3) + 8 * (i >> 2) + 4 * hh; }
; DI void attn_unit(Ctx A_, LAS unsigned char* lds, int b, int h, int qb, float lam, int wave, int lane) {
;     ...
;     l += __shfl_xor(l, 32);
;     if (hh == 0) wsf[32 + r] = l;
;     float rl[16];
; #pragma unroll
;     for (int i = 0; i < 16; ++i) rl[i] = 1.0f / wsf[32 + crow(i, hh)];
;     float lam_e = lam; asm volatile("" : "+v"(lam_e));
;     const float sc = mp == 0 ? 1.0f : lam_e;
; #pragma unroll
;     for (int nb = 0; nb < 4; ++nb)
; #pragma unroll
;         for (int i = 0; i < 16; ++i) o[nb][i] *= rl[i] * sc;
;     asm volatile("s_waitcnt vmcnt(0) lgkmcnt(0)" ::: "memory"); __builtin_amdgcn_s_barrier(); asm volatile("" ::: "memory");
.LBB0_892:
	s_or_b64 exec, exec, s[4:5]
	v_add_u32_e32 v74, s40, v194
	s_waitcnt lgkmcnt(0)
	ds_read_b128 v[66:69], v74 offset:128
	ds_read_b128 v[70:73], v74 offset:160
	s_or_b32 s0, s64, s0
	s_waitcnt lgkmcnt(1)
	v_div_scale_f32 v75, s[4:5], v66, v66, 1.0
	v_rcp_f32_e32 v77, v75
	v_div_scale_f32 v76, vcc, 1.0, v66, 1.0
	v_div_scale_f32 v78, s[4:5], v67, v67, 1.0
	v_fma_f32 v80, -v75, v77, 1.0
	v_fmac_f32_e32 v77, v80, v77
	v_mul_f32_e32 v80, v76, v77
	v_rcp_f32_e32 v79, v78
	v_fma_f32 v81, -v75, v80, v76
	v_fmac_f32_e32 v80, v81, v77
	v_fma_f32 v75, -v75, v80, v76
	v_div_fmas_f32 v75, v75, v77, v80
	v_div_fixup_f32 v80, v75, v66, 1.0
	v_fma_f32 v66, -v78, v79, 1.0
	v_fmac_f32_e32 v79, v66, v79
	v_div_scale_f32 v66, vcc, 1.0, v67, 1.0
	v_mul_f32_e32 v75, v66, v79
	v_fma_f32 v76, -v78, v75, v66
	v_fmac_f32_e32 v75, v76, v79
	v_div_scale_f32 v76, s[4:5], v68, v68, 1.0
	v_rcp_f32_e32 v77, v76
	v_fma_f32 v66, -v78, v75, v66
	v_div_fmas_f32 v66, v66, v79, v75
	v_div_fixup_f32 v78, v66, v67, 1.0
	v_fma_f32 v66, -v76, v77, 1.0
	v_fmac_f32_e32 v77, v66, v77
	v_div_scale_f32 v66, vcc, 1.0, v68, 1.0
	v_mul_f32_e32 v67, v66, v77
	v_fma_f32 v75, -v76, v67, v66
	v_fmac_f32_e32 v67, v75, v77
	v_div_scale_f32 v75, s[4:5], v69, v69, 1.0
	v_fma_f32 v66, -v76, v67, v66
	v_rcp_f32_e32 v76, v75
	v_div_fmas_f32 v66, v66, v77, v67
	v_div_fixup_f32 v79, v66, v68, 1.0
	v_fma_f32 v66, -v75, v76, 1.0
	v_fmac_f32_e32 v76, v66, v76
	v_div_scale_f32 v66, vcc, 1.0, v69, 1.0
	v_mul_f32_e32 v67, v66, v76
	v_fma_f32 v68, -v75, v67, v66
	v_fmac_f32_e32 v67, v68, v76
	s_waitcnt lgkmcnt(0)
	v_div_scale_f32 v68, s[4:5], v70, v70, 1.0
	v_fma_f32 v66, -v75, v67, v66
	v_rcp_f32_e32 v75, v68
	v_div_fmas_f32 v66, v66, v76, v67
	v_div_fixup_f32 v81, v66, v69, 1.0
	v_div_scale_f32 v76, s[4:5], v73, v73, 1.0
	v_fma_f32 v66, -v68, v75, 1.0
	v_fmac_f32_e32 v75, v66, v75
	v_div_scale_f32 v66, vcc, 1.0, v70, 1.0
	v_mul_f32_e32 v67, v66, v75
	v_fma_f32 v69, -v68, v67, v66
	v_fmac_f32_e32 v67, v69, v75
	v_fma_f32 v66, -v68, v67, v66
	v_div_scale_f32 v68, s[4:5], v71, v71, 1.0
	v_rcp_f32_e32 v69, v68
	v_div_fmas_f32 v66, v66, v75, v67
	v_div_fixup_f32 v70, v66, v70, 1.0
	v_rcp_f32_e32 v82, v76
	v_fma_f32 v66, -v68, v69, 1.0
	v_fmac_f32_e32 v69, v66, v69
	v_div_scale_f32 v66, vcc, 1.0, v71, 1.0
	v_mul_f32_e32 v67, v66, v69
	v_fma_f32 v75, -v68, v67, v66
	v_fmac_f32_e32 v67, v75, v69
	v_fma_f32 v66, -v68, v67, v66
	v_div_scale_f32 v68, s[4:5], v72, v72, 1.0
	v_rcp_f32_e32 v75, v68
	v_div_fmas_f32 v66, v66, v69, v67
	v_div_fixup_f32 v71, v66, v71, 1.0
	v_fma_f32 v66, -v68, v75, 1.0
	v_fmac_f32_e32 v75, v66, v75
	v_div_scale_f32 v66, vcc, 1.0, v72, 1.0
	v_mul_f32_e32 v67, v66, v75
	v_fma_f32 v69, -v68, v67, v66
	v_fmac_f32_e32 v67, v69, v75
	v_fma_f32 v66, -v68, v67, v66
	v_div_fmas_f32 v66, v66, v75, v67
	v_div_fixup_f32 v72, v66, v72, 1.0
	v_fma_f32 v66, -v76, v82, 1.0
	v_fmac_f32_e32 v82, v66, v82
	ds_read_b128 v[66:69], v74 offset:192
	v_div_scale_f32 v75, vcc, 1.0, v73, 1.0
	v_mul_f32_e32 v83, v75, v82
	v_fma_f32 v77, -v76, v83, v75
	s_waitcnt lgkmcnt(0)
	v_div_scale_f32 v85, s[4:5], v66, v66, 1.0
	v_rcp_f32_e32 v86, v85
	v_fmac_f32_e32 v83, v77, v82
	v_fma_f32 v84, -v76, v83, v75
	v_div_fmas_f32 v82, v84, v82, v83
	v_div_fixup_f32 v73, v82, v73, 1.0
	v_fma_f32 v82, -v85, v86, 1.0
	v_fmac_f32_e32 v86, v82, v86
	v_div_scale_f32 v82, vcc, 1.0, v66, 1.0
	v_mul_f32_e32 v83, v82, v86
	v_fma_f32 v84, -v85, v83, v82
	v_fmac_f32_e32 v83, v84, v86
	v_div_scale_f32 v84, s[4:5], v67, v67, 1.0
	v_fma_f32 v82, -v85, v83, v82
	v_rcp_f32_e32 v85, v84
	v_div_fmas_f32 v82, v82, v86, v83
	v_div_fixup_f32 v66, v82, v66, 1.0
	ds_read_b128 v[74:77], v74 offset:224
	v_fma_f32 v82, -v84, v85, 1.0
	v_fmac_f32_e32 v85, v82, v85
	v_div_scale_f32 v82, vcc, 1.0, v67, 1.0
	v_mul_f32_e32 v83, v82, v85
	v_fma_f32 v86, -v84, v83, v82
	v_fmac_f32_e32 v83, v86, v85
	v_fma_f32 v82, -v84, v83, v82
	v_div_scale_f32 v84, s[4:5], v68, v68, 1.0
	v_rcp_f32_e32 v86, v84
	v_div_fmas_f32 v82, v82, v85, v83
	v_div_fixup_f32 v67, v82, v67, 1.0
	v_fma_f32 v82, -v84, v86, 1.0
	v_fmac_f32_e32 v86, v82, v86
	v_div_scale_f32 v82, vcc, 1.0, v68, 1.0
	v_mul_f32_e32 v83, v82, v86
	v_fma_f32 v85, -v84, v83, v82
	v_fmac_f32_e32 v83, v85, v86
	v_fma_f32 v82, -v84, v83, v82
	v_div_scale_f32 v84, s[4:5], v69, v69, 1.0
	v_rcp_f32_e32 v85, v84
	v_div_fmas_f32 v82, v82, v86, v83
	v_div_fixup_f32 v68, v82, v68, 1.0
	v_fma_f32 v82, -v84, v85, 1.0
	v_fmac_f32_e32 v85, v82, v85
	v_div_scale_f32 v82, vcc, 1.0, v69, 1.0
	v_mul_f32_e32 v83, v82, v85
	v_fma_f32 v86, -v84, v83, v82
	v_fmac_f32_e32 v83, v86, v85
	v_fma_f32 v82, -v84, v83, v82
	s_waitcnt lgkmcnt(0)
	v_div_scale_f32 v84, s[4:5], v74, v74, 1.0
	v_rcp_f32_e32 v86, v84
	v_div_fmas_f32 v82, v82, v85, v83
	v_div_fixup_f32 v85, v82, v69, 1.0
	v_fma_f32 v69, -v84, v86, 1.0
	v_fmac_f32_e32 v86, v69, v86
	v_div_scale_f32 v69, vcc, 1.0, v74, 1.0
	v_mul_f32_e32 v82, v69, v86
	v_fma_f32 v83, -v84, v82, v69
	v_fmac_f32_e32 v82, v83, v86
	v_div_scale_f32 v83, s[4:5], v75, v75, 1.0
	v_fma_f32 v69, -v84, v82, v69
	v_rcp_f32_e32 v84, v83
	v_div_fmas_f32 v69, v69, v86, v82
	v_div_fixup_f32 v74, v69, v74, 1.0
	v_fma_f32 v69, -v83, v84, 1.0
	v_fmac_f32_e32 v84, v69, v84
	v_div_scale_f32 v69, vcc, 1.0, v75, 1.0
	v_mul_f32_e32 v82, v69, v84
	v_fma_f32 v86, -v83, v82, v69
	v_fmac_f32_e32 v82, v86, v84
	v_fma_f32 v69, -v83, v82, v69
	v_div_scale_f32 v83, s[4:5], v76, v76, 1.0
	v_rcp_f32_e32 v86, v83
	v_div_fmas_f32 v69, v69, v84, v82
	v_div_fixup_f32 v75, v69, v75, 1.0
	v_fma_f32 v69, -v83, v86, 1.0
	v_fmac_f32_e32 v86, v69, v86
	v_div_scale_f32 v69, vcc, 1.0, v76, 1.0
	v_mul_f32_e32 v82, v69, v86
	v_fma_f32 v84, -v83, v82, v69
	v_fmac_f32_e32 v82, v84, v86
	v_fma_f32 v69, -v83, v82, v69
	v_div_scale_f32 v83, s[4:5], v77, v77, 1.0
	v_rcp_f32_e32 v84, v83
	v_div_fmas_f32 v69, v69, v86, v82
	v_div_fixup_f32 v76, v69, v76, 1.0
	v_readlane_b32 s4, v255, 36
	v_fma_f32 v69, -v83, v84, 1.0
	v_fmac_f32_e32 v84, v69, v84
	v_div_scale_f32 v69, vcc, 1.0, v77, 1.0
	v_mul_f32_e32 v82, v69, v84
	v_fma_f32 v86, -v83, v82, v69
	v_fmac_f32_e32 v82, v86, v84
	v_fma_f32 v69, -v83, v82, v69
	v_div_fmas_f32 v69, v69, v84, v82
	v_div_fixup_f32 v77, v69, v77, 1.0
	v_mov_b32_e32 v69, v210
	v_readlane_b32 s5, v255, 37
	s_waitcnt lgkmcnt(0)
	s_barrier
; #define LAS __attribute__((address_space(3)))
; DI void attn_unit(Ctx A_, LAS unsigned char* lds, int b, int h, int qb, float lam, int wave, int lane) {
;     ...
;     const float sc = mp == 0 ? 1.0f : lam_e;
; #pragma unroll
;     for (int nb = 0; nb < 4; ++nb)
; #pragma unroll
;         for (int i = 0; i < 16; ++i) o[nb][i] *= rl[i] * sc;
;     asm volatile("s_waitcnt vmcnt(0) lgkmcnt(0)" ::: "memory"); __builtin_amdgcn_s_barrier(); asm volatile("" ::: "memory");
;     int r_e = r, hh_e = hh; asm volatile("" : "+v"(r_e), "+v"(hh_e));
;     int rowq_e = (int)rowb + q0, h_e = h; asm volatile("" : "+s"(rowq_e), "+s"(h_e));
;     LAS float* X2 = (LAS float*)lds + rg * 4096 + (hh_e * 32 + r_e);
;     if (mp == 1) {
; #pragma unroll
;         for (int nb = 0; nb < 4; ++nb)
; #pragma unroll
;             for (int i = 0; i < 16; ++i) X2[(nb * 16 + i) * 64] = o[nb][i];
;     }
	s_nop 0
	v_cndmask_b32_e64 v86, v69, 1.0, s[4:5]
	v_mul_f32_e32 v81, v81, v86
	v_mul_f32_e32 v89, v37, v81
	v_mul_f32_e32 v37, v70, v86
	v_mul_f32_e32 v92, v78, v86
	v_mul_f32_e32 v96, v79, v86
	v_mul_f32_e32 v88, v38, v37
	v_mul_f32_e32 v38, v71, v86
	v_mul_f32_e32 v73, v73, v86
	v_mul_f32_e32 v105, v75, v86
	v_readlane_b32 s4, v255, 39
	v_mul_f32_e32 v87, v80, v86
	v_mul_f32_e32 v93, v36, v96
	v_mul_f32_e32 v83, v39, v38
	v_mul_f32_e32 v39, v72, v86
	v_mul_f32_e32 v82, v41, v73
	v_mul_f32_e32 v41, v66, v86
	v_mul_f32_e32 v97, v67, v86
	v_mul_f32_e32 v98, v68, v86
	v_mul_f32_e32 v99, v85, v86
	v_mul_f32_e32 v104, v74, v86
	v_mul_f32_e32 v66, v47, v105
	v_mul_f32_e32 v47, v76, v86
	v_mul_f32_e32 v106, v77, v86
	v_mul_f32_e32 v94, v52, v96
	v_mul_f32_e32 v95, v20, v96
	v_mul_f32_e32 v103, v3, v92
	v_mul_f32_e32 v96, v4, v96
	v_lshlrev_b32_e32 v3, 7, v197
	v_lshlrev_b32_e32 v4, 2, v196
	v_readlane_b32 s5, v255, 40
	v_mul_f32_e32 v34, v34, v87
	v_mul_f32_e32 v100, v35, v92
	v_mul_f32_e32 v84, v40, v39
	v_mul_f32_e32 v78, v42, v41
	v_mul_f32_e32 v70, v43, v97
	v_mul_f32_e32 v69, v44, v98
	v_mul_f32_e32 v68, v45, v99
	v_mul_f32_e32 v67, v46, v104
	v_mul_f32_e32 v44, v48, v47
	v_mul_f32_e32 v42, v49, v106
	v_mul_f32_e32 v35, v50, v87
	v_mul_f32_e32 v101, v51, v92
	v_mul_f32_e32 v90, v53, v81
	v_mul_f32_e32 v85, v54, v37
	v_mul_f32_e32 v79, v55, v38
	v_mul_f32_e32 v77, v56, v39
	v_mul_f32_e32 v74, v57, v73
	v_mul_f32_e32 v72, v58, v41
	v_mul_f32_e32 v71, v59, v97
	v_mul_f32_e32 v57, v60, v98
	v_mul_f32_e32 v54, v61, v99
	v_mul_f32_e32 v51, v62, v104
	v_mul_f32_e32 v48, v63, v105
	v_mul_f32_e32 v45, v64, v47
	v_mul_f32_e32 v43, v65, v106
	v_mul_f32_e32 v36, v18, v87
	v_mul_f32_e32 v102, v19, v92
	v_mul_f32_e32 v91, v21, v81
	v_mul_f32_e32 v86, v22, v37
	v_mul_f32_e32 v80, v23, v38
	v_mul_f32_e32 v75, v24, v39
	v_mul_f32_e32 v65, v25, v73
	v_mul_f32_e32 v62, v26, v41
	v_mul_f32_e32 v60, v27, v97
	v_mul_f32_e32 v58, v28, v98
	v_mul_f32_e32 v55, v29, v99
	v_mul_f32_e32 v52, v30, v104
	v_mul_f32_e32 v49, v31, v105
	v_mul_f32_e32 v46, v32, v47
	v_mul_f32_e32 v40, v33, v106
	v_mul_f32_e32 v2, v2, v87
	v_mul_f32_e32 v92, v5, v81
	v_mul_f32_e32 v87, v6, v37
	v_mul_f32_e32 v81, v7, v38
	v_mul_f32_e32 v76, v8, v39
	v_mul_f32_e32 v73, v9, v73
	v_mul_f32_e32 v63, v10, v41
	v_mul_f32_e32 v61, v11, v97
	v_mul_f32_e32 v59, v12, v98
	v_mul_f32_e32 v56, v13, v99
	v_mul_f32_e32 v53, v14, v104
	v_mul_f32_e32 v50, v15, v105
	v_mul_f32_e32 v47, v16, v47
	v_mul_f32_e32 v41, v17, v106
	s_andn2_b64 vcc, exec, s[4:5]
	v_add3_u32 v64, s50, v3, v4
	s_cbranch_vccnz .LBB0_894
	ds_write2st64_b32 v64, v34, v100 offset1:1
	ds_write2st64_b32 v64, v93, v89 offset0:2 offset1:3
	ds_write2st64_b32 v64, v88, v83 offset0:4 offset1:5
	ds_write2st64_b32 v64, v84, v82 offset0:6 offset1:7
	ds_write2st64_b32 v64, v78, v70 offset0:8 offset1:9
	ds_write2st64_b32 v64, v69, v68 offset0:10 offset1:11
	ds_write2st64_b32 v64, v67, v66 offset0:12 offset1:13
	ds_write2st64_b32 v64, v44, v42 offset0:14 offset1:15
	ds_write2st64_b32 v64, v35, v101 offset0:16 offset1:17
	ds_write2st64_b32 v64, v94, v90 offset0:18 offset1:19
	ds_write2st64_b32 v64, v85, v79 offset0:20 offset1:21
	ds_write2st64_b32 v64, v77, v74 offset0:22 offset1:23
	ds_write2st64_b32 v64, v72, v71 offset0:24 offset1:25
	ds_write2st64_b32 v64, v57, v54 offset0:26 offset1:27
	ds_write2st64_b32 v64, v51, v48 offset0:28 offset1:29
	ds_write2st64_b32 v64, v45, v43 offset0:30 offset1:31
	ds_write2st64_b32 v64, v36, v102 offset0:32 offset1:33
	ds_write2st64_b32 v64, v95, v91 offset0:34 offset1:35
	ds_write2st64_b32 v64, v86, v80 offset0:36 offset1:37
	ds_write2st64_b32 v64, v75, v65 offset0:38 offset1:39
	ds_write2st64_b32 v64, v62, v60 offset0:40 offset1:41
	ds_write2st64_b32 v64, v58, v55 offset0:42 offset1:43
	ds_write2st64_b32 v64, v52, v49 offset0:44 offset1:45
	ds_write2st64_b32 v64, v46, v40 offset0:46 offset1:47
	ds_write2st64_b32 v64, v2, v103 offset0:48 offset1:49
	ds_write2st64_b32 v64, v96, v92 offset0:50 offset1:51
	ds_write2st64_b32 v64, v87, v81 offset0:52 offset1:53
	ds_write2st64_b32 v64, v76, v73 offset0:54 offset1:55
	ds_write2st64_b32 v64, v63, v61 offset0:56 offset1:57
	ds_write2st64_b32 v64, v59, v56 offset0:58 offset1:59
	ds_write2st64_b32 v64, v53, v50 offset0:60 offset1:61
	ds_write2st64_b32 v64, v47, v41 offset0:62 offset1:63

; #define LAS __attribute__((address_space(3)))
; DI int tid_now() { int t; asm volatile("v_mov_b32 %0, %1" : "=v"(t) : "v"((int)threadIdx.x)); return t; }
; #define PROBE_T0(k) unsigned long long pt0_ = 0; if ((k) == PROBE_PH) pt0_ = __builtin_amdgcn_s_memrealtime();
; #define Q_NEXT(k, id) do { if (tid == 0) qw[qit & 1] = __hip_atomic_fetch_add(qctr + 64 * (k), 1u, __ATOMIC_RELAXED, __HIP_MEMORY_SCOPE_AGENT); __syncthreads(); \
;         id = __builtin_amdgcn_readfirstlane((int)qw[qit & 1]); ++qit; } while (0)
; DI void cross_unit(Ctx A_, LAS unsigned char* lds, int kvb, int hc, size_t row0, int nrows, int wave, int lane) {
;     const int r = lane & 31, hh = lane >> 5, rg = wave & 3, dvh = wave >> 2;
;     bf16* P = P_;
;     const bf16* Kg = MKV_ + (size_t)kvb * NMEM * 2048 + hc * 256; const bf16* Vg = Kg + 1024;
;     LAS float* wsf = (LAS float*)(lds + WSF_OFF) + wave * 128;
;     const bool act = rg * 32 < nrows;
;     load_tile(lds, Kg, Vg, 0, wave, lane);
;     bf16x8 qr[16];
;     { const bf16* Qg = P + (row0 + rg * 32 + r) * PLD + C_QC + hc * 256 + hh * 8;
; #pragma unroll
;       for (int d0 = 0; d0 < 16; ++d0) qr[d0] = *(const bf16x8*)(Qg + d0 * 16); }
;     asm volatile("" : "+v"(qr[0]), "+v"(qr[1]), "+v"(qr[2]), "+v"(qr[3]), "+v"(qr[4]), "+v"(qr[5]), "+v"(qr[6]), "+v"(qr[7]), "+v"(qr[8]), "+v"(qr[9]), "+v"(qr[10]), "+v"(qr[11]), "+v"(qr[12]), "+v"(qr[13]), "+v"(qr[14]), "+v"(qr[15]));
; __global__ void __launch_bounds__(512, 2) fwd(Args args) {
;     ...
;         { PROBE_T0(23)
; #pragma unroll 1
;         for (;;) { int id; Q_NEXT(3, id); if (id >= 1152) break; const int lane = tid_now() & 63;
;             if (id < 1024) { const int qb = id & 31, hc = (id >> 5) & 3, b = id >> 7; ca::cross_unit(A_, lds, b, hc, (size_t)b * SEQ + qb * 128, 128, wave, lane); }
;             else { const int sidx = id - 1024, hc = sidx & 3, b = sidx >> 2; ca::cross_unit(A_, lds, 8 + b, hc, (size_t)MP + b * DS, DS, wave, lane); } }
.LBB0_896:
	v_readlane_b32 s12, v254, 60
	v_readlane_b32 s14, v254, 62
	v_readlane_b32 s15, v254, 63
	s_add_u32 s0, s14, 0x20300
	s_addc_u32 s1, s15, 0
	s_add_u32 s42, s14, 0x17600000
	s_addc_u32 s43, s15, 0
	s_and_b32 s44, s80, 0x60
	s_lshl_b32 s45, s27, 4
	s_bfe_i64 s[4:5], s[80:81], 0x200000
	s_add_i32 s47, s37, 0x4000
	s_add_i32 s48, s37, 0x4400
	s_cmp_eq_u32 s44, 0
	s_cselect_b64 s[6:7], -1, 0
	s_lshl_b32 s8, s84, 7
	s_ashr_i32 s9, s8, 31
	s_lshl_b64 s[8:9], s[8:9], 1
	v_readlane_b32 s10, v255, 9
	v_readlane_b32 s11, v255, 10
	s_add_u32 s49, s10, s8
	s_addc_u32 s50, s11, s9
	s_add_u32 s51, s14, s8
	s_addc_u32 s52, s15, s9
	s_add_u32 s53, s51, 0x64901000
	s_addc_u32 s54, s52, 0
	s_lshl_b64 s[8:9], s[4:5], 1
	s_add_u32 s2, s14, s8
	s_addc_u32 s4, s15, s9
	s_add_u32 s10, s2, 0x17e20800
	s_addc_u32 s11, s4, 0
	s_add_u32 s55, s14, 0x17e20000
	s_addc_u32 s56, s15, 0
	v_readlane_b32 s13, v254, 61
	s_add_u32 s12, s2, 0x17620800
	s_addc_u32 s13, s4, 0
	s_add_u32 s57, s14, 0x17620000
	s_movk_i32 s46, 0x4000
	s_mov_b32 s3, 0
	s_addc_u32 s58, s15, 0
	v_mov_b32_e32 v3, 0
	s_mov_b64 s[14:15], 0x800
	s_mov_b64 s[16:17], 0x10800
	s_movk_i32 s59, 0x5800
	s_mov_b64 s[18:19], 0x4800
	s_mov_b64 s[20:21], 0x10000
	s_mov_b64 s[22:23], 0x20000
	s_movk_i32 s60, 0x5000
	s_movk_i32 s61, 0x7fff
	s_movk_i32 s62, 0x1800
	s_mov_b64 s[24:25], 0x64901040
	s_mov_b64 s[26:27], 0x64901080
	s_mov_b64 s[28:29], 0x649010c0
	s_waitcnt vmcnt(2)
	v_mov_b32_e32 v165, 0x5800
	s_and_saveexec_b64 s[4:5], s[82:83]
	s_cbranch_execz .Lcross_q_pre
	s_waitcnt vmcnt(0)
	v_mov_b32_e32 v205, 1
	s_nop 0
	global_atomic_add v205, v3, v205, s[0:1] sc0
	s_waitcnt vmcnt(0)

; DI float bf2f(unsigned short u) { return __uint_as_float((unsigned)u << 16); }
; DI unsigned f2bf(float f) { unsigned u = __float_as_uint(f); return (u + 0x7fffu + ((u >> 16) & 1u)) >> 16; }
; DI int crow(int i, int hh) { return (i & 3) + 8 * (i >> 2) + 4 * hh; }
; DI void cross_unit(Ctx A_, LAS unsigned char* lds, int kvb, int hc, size_t row0, int nrows, int wave, int lane) {
;     ...
;     if (act) {
;         l += __shfl_xor(l, 32);
;         if (hh == 0) wsf[32 + r] = l;
;         float rl[16];
; #pragma unroll
;         for (int i = 0; i < 16; ++i) rl[i] = 1.0f / wsf[32 + crow(i, hh)];
; #pragma unroll
;         for (int nb = 0; nb < 4; ++nb)
; #pragma unroll
;             for (int i = 0; i < 16; ++i) {
;                 const int q = rg * 32 + crow(i, hh);
;                 if (q < nrows) { const size_t eo = (row0 + q) * PLD + hc * 256 + dvh * 128 + nb * 32 + r; Y_[(row0 + q) * YLD + C_YC + hc * 256 + dvh * 128 + nb * 32 + r] = (bf16)f2bf(o[nb][i] * rl[i] * bf2f(P[eo + C_ZC])); }
;             }
.LBB0_897:
	s_or_b64 exec, exec, s[34:35]
	s_waitcnt vmcnt(0)
	v_and_b32_e32 v206, 63, v0
	v_lshrrev_b32_e32 v207, 5, v206
	v_and_b32_e32 v206, 31, v206
	v_lshlrev_b32_e32 v206, 1, v206
	v_lshl_or_b32 v206, v207, 10, v206
	v_readfirstlane_b32 s98, v0
	s_lshr_b32 s98, s98, 6
	s_lshl_b32 s98, s98, 13
	s_add_i32 s98, s98, 0x10000
	v_add_u32_e32 v206, s98, v206
	s_lshl_b32 s4, s64, 1
	s_add_u32 s34, s49, s4
	v_lshl_or_b32 v4, v174, 2, s44
	s_addc_u32 s35, s50, 0
	s_waitcnt lgkmcnt(0)
	v_lshlrev_b32_e32 v2, 1, v164
	v_lshl_add_u64 v[8:9], s[34:35], 0, v[2:3]
	v_or_b32_e32 v82, s30, v4
	v_mad_u64_u32 v[4:5], s[34:35], v82, s59, v[8:9]
	s_mul_i32 s2, s31, 0x5800
	v_add_u32_e32 v5, s2, v5
	v_add_co_u32_e32 v4, vcc, s60, v4
	v_add_u32_e32 v101, s40, v162
	s_nop 0
	v_addc_co_u32_e32 v5, vcc, 0, v5, vcc
	ds_read_u16 v83, v206 offset:0
	ds_read_u16 v98, v206 offset:64
	ds_read_u16 v99, v206 offset:128
	ds_read_u16 v100, v206 offset:192
	ds_read_b128 v[84:87], v101 offset:128
	ds_read_b128 v[4:7], v101 offset:160
	s_add_u32 s34, s53, s4
	s_addc_u32 s35, s54, 0
	v_lshl_add_u64 v[10:11], s[34:35], 0, v[2:3]
	s_add_u32 s34, s51, s4
	s_waitcnt lgkmcnt(1)
	v_div_scale_f32 v103, s[4:5], v84, v84, 1.0
	v_rcp_f32_e32 v105, v103
	v_or_b32_e32 v102, 1, v82
	v_mad_u64_u32 v[12:13], s[64:65], v102, s59, v[8:9]
	v_mad_u64_u32 v[88:89], s[4:5], v82, s62, v[10:11]
	v_add_u32_e32 v13, s2, v13
	v_add_co_u32_e64 v90, s[4:5], s60, v12
	s_addc_u32 s35, s52, 0
	s_nop 0
	v_addc_co_u32_e64 v91, s[4:5], 0, v13, s[4:5]
	v_lshl_add_u64 v[12:13], s[34:35], 0, v[2:3]
	v_fma_f32 v2, -v103, v105, 1.0
	v_div_scale_f32 v104, vcc, 1.0, v84, 1.0
	v_fmac_f32_e32 v105, v2, v105
	v_mul_f32_e32 v2, v104, v105
	v_fma_f32 v106, -v103, v2, v104
	v_fmac_f32_e32 v2, v106, v105
	v_fma_f32 v103, -v103, v2, v104
	v_div_fmas_f32 v2, v103, v105, v2
	v_div_fixup_f32 v2, v2, v84, 1.0
	v_mul_f32_e32 v18, v18, v2
	v_mul_f32_e32 v34, v34, v2
	v_mul_f32_e32 v50, v50, v2
	v_mul_f32_e32 v2, v66, v2
	s_mul_i32 s30, s31, 0x1800
	v_lshl_add_u64 v[14:15], v[12:13], 0, s[24:25]
	v_lshl_add_u64 v[16:17], v[12:13], 0, s[26:27]
	v_lshl_add_u64 v[12:13], v[12:13], 0, s[28:29]
	v_add_u32_e32 v89, s30, v89
	v_mad_u64_u32 v[92:93], s[4:5], v82, s62, v[14:15]
	v_mad_u64_u32 v[94:95], s[4:5], v82, s62, v[16:17]
	v_mad_u64_u32 v[96:97], s[4:5], v82, s62, v[12:13]
	v_add_u32_e32 v93, s30, v93
	v_add_u32_e32 v95, s30, v95
	v_add_u32_e32 v97, s30, v97
	s_waitcnt lgkmcnt(0)
	v_lshlrev_b32_e32 v66, 16, v83
	s_waitcnt lgkmcnt(0)
	v_lshlrev_b32_e32 v83, 16, v98
	s_waitcnt lgkmcnt(0)
	v_lshlrev_b32_e32 v84, 16, v99
	s_waitcnt lgkmcnt(0)
	v_lshlrev_b32_e32 v98, 16, v100
	v_mul_f32_e32 v18, v18, v66
	v_mul_f32_e32 v34, v34, v83
	v_mul_f32_e32 v50, v50, v84
	v_mul_f32_e32 v2, v2, v98
	v_bfe_u32 v66, v18, 16, 1
	v_bfe_u32 v83, v34, 16, 1
	v_bfe_u32 v84, v50, 16, 1
	v_bfe_u32 v98, v2, 16, 1
	v_add3_u32 v18, v18, v66, s61
	v_add3_u32 v34, v34, v83, s61
	v_add3_u32 v50, v50, v84, s61
	v_add3_u32 v2, v2, v98, s61
	ds_write_b16_d16_hi v206, v18 offset:0
	ds_write_b16_d16_hi v206, v34 offset:64
	ds_write_b16_d16_hi v206, v50 offset:128
	ds_write_b16_d16_hi v206, v2 offset:192
	ds_read_u16 v2, v206 offset:256
	s_nop 0
	ds_read_u16 v18, v206 offset:320
	ds_read_u16 v34, v206 offset:384
	ds_read_u16 v50, v206 offset:448
	v_or_b32_e32 v83, 2, v82
	v_mad_u64_u32 v[88:89], s[4:5], v83, s59, v[8:9]
	v_div_scale_f32 v84, s[4:5], v85, v85, 1.0
	v_mad_u64_u32 v[90:91], s[4:5], v102, s62, v[10:11]
	v_add_u32_e32 v66, s2, v89
	v_add_co_u32_e64 v88, s[4:5], s60, v88
	v_div_scale_f32 v98, vcc, 1.0, v85, 1.0
	s_nop 0
	v_addc_co_u32_e64 v89, s[4:5], 0, v66, s[4:5]
	v_rcp_f32_e32 v66, v84
	v_add_u32_e32 v91, s30, v91
	v_mad_u64_u32 v[92:93], s[4:5], v102, s62, v[14:15]
	v_fma_f32 v99, -v84, v66, 1.0
	v_fmac_f32_e32 v66, v99, v66
	v_mul_f32_e32 v99, v98, v66
	v_fma_f32 v100, -v84, v99, v98
	v_fmac_f32_e32 v99, v100, v66
	v_fma_f32 v84, -v84, v99, v98
	v_div_fmas_f32 v66, v84, v66, v99
	v_div_fixup_f32 v66, v66, v85, 1.0
	v_mul_f32_e32 v19, v19, v66
	v_mul_f32_e32 v35, v35, v66
	v_mul_f32_e32 v51, v51, v66
	v_mul_f32_e32 v66, v67, v66
	v_mad_u64_u32 v[94:95], s[4:5], v102, s62, v[16:17]
	v_mad_u64_u32 v[96:97], s[4:5], v102, s62, v[12:13]
	v_add_u32_e32 v93, s30, v93
	v_add_u32_e32 v95, s30, v95
	v_add_u32_e32 v97, s30, v97
	s_waitcnt lgkmcnt(0)
	v_lshlrev_b32_e32 v2, 16, v2
	s_waitcnt lgkmcnt(0)
	v_lshlrev_b32_e32 v18, 16, v18
	s_waitcnt lgkmcnt(0)
	v_lshlrev_b32_e32 v34, 16, v34
	s_waitcnt lgkmcnt(0)
	v_lshlrev_b32_e32 v50, 16, v50
	v_mul_f32_e32 v2, v19, v2
	v_mul_f32_e32 v18, v35, v18
	v_mul_f32_e32 v19, v51, v34
	v_mul_f32_e32 v34, v66, v50
	v_bfe_u32 v35, v2, 16, 1
	v_bfe_u32 v50, v18, 16, 1
	v_bfe_u32 v51, v19, 16, 1
	v_bfe_u32 v66, v34, 16, 1
	v_add3_u32 v2, v2, v35, s61
	v_add3_u32 v18, v18, v50, s61
	v_add3_u32 v19, v19, v51, s61
	v_add3_u32 v34, v34, v66, s61
	ds_write_b16_d16_hi v206, v2 offset:256
	ds_write_b16_d16_hi v206, v18 offset:320
	ds_write_b16_d16_hi v206, v19 offset:384
	ds_write_b16_d16_hi v206, v34 offset:448
	ds_read_u16 v2, v206 offset:512
	s_nop 0
	ds_read_u16 v90, v206 offset:576
	ds_read_u16 v91, v206 offset:640
	s_nop 0
	ds_read_u16 v88, v206 offset:704
	v_div_scale_f32 v92, s[4:5], v86, v86, 1.0
	v_rcp_f32_e32 v94, v92
	v_or_b32_e32 v89, 3, v82
	v_mad_u64_u32 v[18:19], s[4:5], v89, s59, v[8:9]
	v_mad_u64_u32 v[34:35], s[4:5], v83, s62, v[10:11]
	v_add_u32_e32 v19, s2, v19
	v_add_co_u32_e64 v18, s[4:5], s60, v18
	v_div_scale_f32 v93, vcc, 1.0, v86, 1.0
	s_nop 0
	v_addc_co_u32_e64 v19, s[4:5], 0, v19, s[4:5]
	v_mad_u64_u32 v[50:51], s[4:5], v83, s62, v[14:15]
	v_mad_u64_u32 v[66:67], s[4:5], v83, s62, v[16:17]
	v_mad_u64_u32 v[84:85], s[4:5], v83, s62, v[12:13]
	v_fma_f32 v83, -v92, v94, 1.0
	v_fmac_f32_e32 v94, v83, v94
	v_mul_f32_e32 v83, v93, v94
	v_fma_f32 v95, -v92, v83, v93
	v_fmac_f32_e32 v83, v95, v94
	v_fma_f32 v92, -v92, v83, v93
	v_div_fmas_f32 v83, v92, v94, v83
	v_div_fixup_f32 v83, v83, v86, 1.0
	v_mul_f32_e32 v20, v20, v83
	v_mul_f32_e32 v36, v36, v83
	v_mul_f32_e32 v52, v52, v83
	v_mul_f32_e32 v68, v68, v83
	v_add_u32_e32 v35, s30, v35
	v_add_u32_e32 v51, s30, v51
	v_add_u32_e32 v67, s30, v67
	v_add_u32_e32 v85, s30, v85
	s_waitcnt lgkmcnt(0)
; DI float bf2f(unsigned short u) { return __uint_as_float((unsigned)u << 16); }
; DI unsigned f2bf(float f) { unsigned u = __float_as_uint(f); return (u + 0x7fffu + ((u >> 16) & 1u)) >> 16; }
; DI int crow(int i, int hh) { return (i & 3) + 8 * (i >> 2) + 4 * hh; }
; DI void cross_unit(Ctx A_, LAS unsigned char* lds, int kvb, int hc, size_t row0, int nrows, int wave, int lane) {
;     ...
; #pragma unroll
;         for (int nb = 0; nb < 4; ++nb)
; #pragma unroll
;             for (int i = 0; i < 16; ++i) {
;                 const int q = rg * 32 + crow(i, hh);
;                 if (q < nrows) { const size_t eo = (row0 + q) * PLD + hc * 256 + dvh * 128 + nb * 32 + r; Y_[(row0 + q) * YLD + C_YC + hc * 256 + dvh * 128 + nb * 32 + r] = (bf16)f2bf(o[nb][i] * rl[i] * bf2f(P[eo + C_ZC])); }
;             }
	v_lshlrev_b32_e32 v2, 16, v2
	s_waitcnt lgkmcnt(0)
	v_lshlrev_b32_e32 v83, 16, v90
	s_waitcnt lgkmcnt(0)
	v_lshlrev_b32_e32 v86, 16, v91
	s_waitcnt lgkmcnt(0)
	v_lshlrev_b32_e32 v88, 16, v88
	v_mul_f32_e32 v2, v20, v2
	v_mul_f32_e32 v20, v36, v83
	v_mul_f32_e32 v36, v52, v86
	v_mul_f32_e32 v52, v68, v88
	v_bfe_u32 v68, v2, 16, 1
	v_bfe_u32 v83, v20, 16, 1
	v_bfe_u32 v86, v36, 16, 1
	v_bfe_u32 v88, v52, 16, 1
	v_add3_u32 v2, v2, v68, s61
	v_add3_u32 v20, v20, v83, s61
	v_add3_u32 v36, v36, v86, s61
	v_add3_u32 v52, v52, v88, s61
	ds_write_b16_d16_hi v206, v2 offset:512
	ds_write_b16_d16_hi v206, v20 offset:576
	ds_write_b16_d16_hi v206, v36 offset:640
	ds_write_b16_d16_hi v206, v52 offset:704
	ds_read_u16 v2, v206 offset:768
	s_nop 0
	ds_read_u16 v20, v206 offset:832
	ds_read_u16 v36, v206 offset:896
	ds_read_u16 v52, v206 offset:960
	v_div_scale_f32 v83, s[4:5], v87, v87, 1.0
	v_rcp_f32_e32 v88, v83
	v_or_b32_e32 v68, 8, v82
	v_mad_u64_u32 v[18:19], s[4:5], v68, s59, v[8:9]
	v_mad_u64_u32 v[34:35], s[4:5], v89, s62, v[10:11]
	v_add_u32_e32 v19, s2, v19
	v_add_co_u32_e64 v18, s[4:5], s60, v18
	v_div_scale_f32 v86, vcc, 1.0, v87, 1.0
	s_nop 0
	v_addc_co_u32_e64 v19, s[4:5], 0, v19, s[4:5]
	v_mad_u64_u32 v[50:51], s[4:5], v89, s62, v[14:15]
	v_mad_u64_u32 v[66:67], s[4:5], v89, s62, v[16:17]
	v_mad_u64_u32 v[84:85], s[4:5], v89, s62, v[12:13]
	v_fma_f32 v89, -v83, v88, 1.0
	v_fmac_f32_e32 v88, v89, v88
	v_mul_f32_e32 v89, v86, v88
	v_fma_f32 v90, -v83, v89, v86
	v_fmac_f32_e32 v89, v90, v88
	v_fma_f32 v83, -v83, v89, v86
	v_div_fmas_f32 v83, v83, v88, v89
	v_div_fixup_f32 v83, v83, v87, 1.0
	v_mul_f32_e32 v21, v21, v83
	v_mul_f32_e32 v37, v37, v83
	v_mul_f32_e32 v53, v53, v83
	v_mul_f32_e32 v69, v69, v83
	v_add_u32_e32 v35, s30, v35
	v_add_u32_e32 v51, s30, v51
	v_add_u32_e32 v67, s30, v67
	v_add_u32_e32 v85, s30, v85
	s_waitcnt lgkmcnt(0)
	v_div_scale_f32 v83, vcc, 1.0, v4, 1.0
	s_waitcnt lgkmcnt(0)
	v_lshlrev_b32_e32 v2, 16, v2
	s_waitcnt lgkmcnt(0)
	v_lshlrev_b32_e32 v20, 16, v20
	s_waitcnt lgkmcnt(0)
	v_lshlrev_b32_e32 v36, 16, v36
	s_waitcnt lgkmcnt(0)
	v_lshlrev_b32_e32 v52, 16, v52
	v_mul_f32_e32 v2, v21, v2
	v_mul_f32_e32 v20, v37, v20
	v_mul_f32_e32 v21, v53, v36
	v_mul_f32_e32 v36, v69, v52
	v_bfe_u32 v37, v2, 16, 1
	v_bfe_u32 v52, v20, 16, 1
	v_bfe_u32 v53, v21, 16, 1
	v_bfe_u32 v69, v36, 16, 1
	v_add3_u32 v2, v2, v37, s61
	v_add3_u32 v20, v20, v52, s61
	v_add3_u32 v21, v21, v53, s61
	v_add3_u32 v36, v36, v69, s61
	ds_write_b16_d16_hi v206, v2 offset:768
	ds_write_b16_d16_hi v206, v20 offset:832
	ds_write_b16_d16_hi v206, v21 offset:896
	ds_write_b16_d16_hi v206, v36 offset:960
	ds_read_u16 v2, v206 offset:2048
	s_nop 0
	ds_read_u16 v52, v206 offset:2112
	ds_read_u16 v53, v206 offset:2176
	ds_read_u16 v66, v206 offset:2240
	v_div_scale_f32 v69, s[4:5], v4, v4, 1.0
	v_rcp_f32_e32 v84, v69
	v_or_b32_e32 v67, 9, v82
	v_mad_u64_u32 v[18:19], s[4:5], v67, s59, v[8:9]
	v_mad_u64_u32 v[20:21], s[4:5], v68, s62, v[10:11]
	v_add_u32_e32 v19, s2, v19
	v_add_co_u32_e64 v18, s[4:5], s60, v18
	v_add_u32_e32 v21, s30, v21
	s_nop 0
	v_addc_co_u32_e64 v19, s[4:5], 0, v19, s[4:5]
	v_mad_u64_u32 v[34:35], s[4:5], v68, s62, v[14:15]
	v_mad_u64_u32 v[36:37], s[4:5], v68, s62, v[16:17]
	v_mad_u64_u32 v[50:51], s[4:5], v68, s62, v[12:13]
	v_fma_f32 v68, -v69, v84, 1.0
	v_fmac_f32_e32 v84, v68, v84
	v_mul_f32_e32 v68, v83, v84
	v_fma_f32 v85, -v69, v68, v83
	v_fmac_f32_e32 v68, v85, v84
	v_fma_f32 v69, -v69, v68, v83
	v_div_fmas_f32 v68, v69, v84, v68
	v_div_fixup_f32 v4, v68, v4, 1.0
	v_mul_f32_e32 v22, v22, v4
	v_mul_f32_e32 v38, v38, v4
	v_mul_f32_e32 v54, v54, v4
	v_mul_f32_e32 v4, v70, v4
	v_add_u32_e32 v35, s30, v35
	v_add_u32_e32 v37, s30, v37
	v_add_u32_e32 v51, s30, v51
	s_waitcnt lgkmcnt(0)
	v_lshlrev_b32_e32 v2, 16, v2
	s_waitcnt lgkmcnt(0)
	v_lshlrev_b32_e32 v52, 16, v52
	s_waitcnt lgkmcnt(0)
	v_lshlrev_b32_e32 v53, 16, v53
	s_waitcnt lgkmcnt(0)
	v_lshlrev_b32_e32 v66, 16, v66
	v_mul_f32_e32 v2, v22, v2
	v_mul_f32_e32 v22, v38, v52
	v_mul_f32_e32 v38, v54, v53
	v_mul_f32_e32 v4, v4, v66
	v_bfe_u32 v52, v2, 16, 1
	v_bfe_u32 v53, v22, 16, 1
	v_bfe_u32 v54, v38, 16, 1
	v_bfe_u32 v66, v4, 16, 1
	v_add3_u32 v2, v2, v52, s61
	v_add3_u32 v22, v22, v53, s61
	v_add3_u32 v38, v38, v54, s61
	v_add3_u32 v4, v4, v66, s61
	ds_write_b16_d16_hi v206, v2 offset:2048
	ds_write_b16_d16_hi v206, v22 offset:2112
	ds_write_b16_d16_hi v206, v38 offset:2176
	ds_write_b16_d16_hi v206, v4 offset:2240
	ds_read_u16 v2, v206 offset:2304
	s_nop 0
	ds_read_u16 v4, v206 offset:2368
	ds_read_u16 v22, v206 offset:2432
	ds_read_u16 v38, v206 offset:2496
	v_div_scale_f32 v53, s[4:5], v5, v5, 1.0
	v_rcp_f32_e32 v66, v53
	v_or_b32_e32 v52, 10, v82
	v_mad_u64_u32 v[18:19], s[4:5], v52, s59, v[8:9]
	v_mad_u64_u32 v[20:21], s[4:5], v67, s62, v[10:11]
	v_add_u32_e32 v19, s2, v19
	v_add_co_u32_e64 v18, s[4:5], s60, v18
	v_div_scale_f32 v54, vcc, 1.0, v5, 1.0
	s_nop 0
	v_addc_co_u32_e64 v19, s[4:5], 0, v19, s[4:5]
	v_mad_u64_u32 v[34:35], s[4:5], v67, s62, v[14:15]
	v_mad_u64_u32 v[36:37], s[4:5], v67, s62, v[16:17]
	v_mad_u64_u32 v[50:51], s[4:5], v67, s62, v[12:13]
	v_fma_f32 v67, -v53, v66, 1.0
	v_fmac_f32_e32 v66, v67, v66
	v_mul_f32_e32 v67, v54, v66
	v_fma_f32 v68, -v53, v67, v54
	v_fmac_f32_e32 v67, v68, v66
	v_fma_f32 v53, -v53, v67, v54
	v_div_fmas_f32 v53, v53, v66, v67
	v_div_fixup_f32 v5, v53, v5, 1.0
	v_mul_f32_e32 v23, v23, v5
	v_mul_f32_e32 v39, v39, v5
	v_mul_f32_e32 v53, v55, v5
	v_mul_f32_e32 v5, v71, v5
	v_add_u32_e32 v21, s30, v21
	v_add_u32_e32 v35, s30, v35
	v_add_u32_e32 v37, s30, v37
	v_add_u32_e32 v51, s30, v51
	s_waitcnt lgkmcnt(0)
; DI float bf2f(unsigned short u) { return __uint_as_float((unsigned)u << 16); }
; DI unsigned f2bf(float f) { unsigned u = __float_as_uint(f); return (u + 0x7fffu + ((u >> 16) & 1u)) >> 16; }
; DI int crow(int i, int hh) { return (i & 3) + 8 * (i >> 2) + 4 * hh; }
; DI void cross_unit(Ctx A_, LAS unsigned char* lds, int kvb, int hc, size_t row0, int nrows, int wave, int lane) {
;     ...
; #pragma unroll
;         for (int nb = 0; nb < 4; ++nb)
; #pragma unroll
;             for (int i = 0; i < 16; ++i) {
;                 const int q = rg * 32 + crow(i, hh);
;                 if (q < nrows) { const size_t eo = (row0 + q) * PLD + hc * 256 + dvh * 128 + nb * 32 + r; Y_[(row0 + q) * YLD + C_YC + hc * 256 + dvh * 128 + nb * 32 + r] = (bf16)f2bf(o[nb][i] * rl[i] * bf2f(P[eo + C_ZC])); }
;             }
	v_lshlrev_b32_e32 v2, 16, v2
	s_waitcnt lgkmcnt(0)
	v_lshlrev_b32_e32 v4, 16, v4
	s_waitcnt lgkmcnt(0)
	v_lshlrev_b32_e32 v22, 16, v22
	s_waitcnt lgkmcnt(0)
	v_lshlrev_b32_e32 v38, 16, v38
	v_mul_f32_e32 v2, v23, v2
	v_mul_f32_e32 v4, v39, v4
	v_mul_f32_e32 v22, v53, v22
	v_mul_f32_e32 v5, v5, v38
	v_bfe_u32 v23, v2, 16, 1
	v_bfe_u32 v38, v4, 16, 1
	v_bfe_u32 v39, v22, 16, 1
	v_bfe_u32 v53, v5, 16, 1
	v_add3_u32 v2, v2, v23, s61
	v_add3_u32 v4, v4, v38, s61
	v_add3_u32 v22, v22, v39, s61
	v_add3_u32 v5, v5, v53, s61
	ds_write_b16_d16_hi v206, v2 offset:2304
	ds_write_b16_d16_hi v206, v4 offset:2368
	ds_write_b16_d16_hi v206, v22 offset:2432
	ds_write_b16_d16_hi v206, v5 offset:2496
	ds_read_u16 v2, v206 offset:2560
	s_nop 0
	ds_read_u16 v36, v206 offset:2624
	ds_read_u16 v37, v206 offset:2688
	ds_read_u16 v38, v206 offset:2752
	v_div_scale_f32 v50, s[4:5], v6, v6, 1.0
	v_rcp_f32_e32 v53, v50
	v_or_b32_e32 v39, 11, v82
	v_mad_u64_u32 v[4:5], s[4:5], v39, s59, v[8:9]
	v_mad_u64_u32 v[18:19], s[4:5], v52, s62, v[10:11]
	v_add_u32_e32 v5, s2, v5
	v_add_co_u32_e64 v4, s[4:5], s60, v4
	v_div_scale_f32 v51, vcc, 1.0, v6, 1.0
	s_nop 0
	v_addc_co_u32_e64 v5, s[4:5], 0, v5, s[4:5]
	v_mad_u64_u32 v[20:21], s[4:5], v52, s62, v[14:15]
	v_mad_u64_u32 v[22:23], s[4:5], v52, s62, v[16:17]
	v_mad_u64_u32 v[34:35], s[4:5], v52, s62, v[12:13]
	v_fma_f32 v52, -v50, v53, 1.0
	v_fmac_f32_e32 v53, v52, v53
	v_mul_f32_e32 v52, v51, v53
	v_fma_f32 v54, -v50, v52, v51
	v_fmac_f32_e32 v52, v54, v53
	v_fma_f32 v50, -v50, v52, v51
	v_div_fmas_f32 v50, v50, v53, v52
	v_div_fixup_f32 v6, v50, v6, 1.0
	v_mul_f32_e32 v24, v24, v6
	v_mul_f32_e32 v40, v40, v6
	v_mul_f32_e32 v50, v56, v6
	v_mul_f32_e32 v6, v72, v6
	v_add_u32_e32 v19, s30, v19
	v_add_u32_e32 v21, s30, v21
	v_add_u32_e32 v23, s30, v23
	v_add_u32_e32 v35, s30, v35
	s_waitcnt lgkmcnt(0)
	v_lshlrev_b32_e32 v2, 16, v2
	s_waitcnt lgkmcnt(0)
	v_lshlrev_b32_e32 v36, 16, v36
	s_waitcnt lgkmcnt(0)
	v_lshlrev_b32_e32 v37, 16, v37
	s_waitcnt lgkmcnt(0)
	v_lshlrev_b32_e32 v38, 16, v38
	v_mul_f32_e32 v2, v24, v2
	v_mul_f32_e32 v24, v40, v36
	v_mul_f32_e32 v36, v50, v37
	v_mul_f32_e32 v6, v6, v38
	v_bfe_u32 v37, v2, 16, 1
	v_bfe_u32 v38, v24, 16, 1
	v_bfe_u32 v40, v36, 16, 1
	v_bfe_u32 v50, v6, 16, 1
	v_add3_u32 v2, v2, v37, s61
	v_add3_u32 v24, v24, v38, s61
	v_add3_u32 v36, v36, v40, s61
	v_add3_u32 v6, v6, v50, s61
	ds_write_b16_d16_hi v206, v2 offset:2560
	ds_write_b16_d16_hi v206, v24 offset:2624
	ds_write_b16_d16_hi v206, v36 offset:2688
	ds_write_b16_d16_hi v206, v6 offset:2752
	ds_read_u16 v2, v206 offset:2816
	s_nop 0
	ds_read_u16 v6, v206 offset:2880
	ds_read_u16 v24, v206 offset:2944
	ds_read_u16 v36, v206 offset:3008
	v_div_scale_f32 v37, s[4:5], v7, v7, 1.0
	v_rcp_f32_e32 v50, v37
	v_or_b32_e32 v38, 16, v82
	v_mad_u64_u32 v[4:5], s[4:5], v38, s59, v[8:9]
	v_mad_u64_u32 v[18:19], s[4:5], v39, s62, v[10:11]
	v_add_u32_e32 v5, s2, v5
	v_add_co_u32_e64 v4, s[4:5], s60, v4
	v_div_scale_f32 v40, vcc, 1.0, v7, 1.0
	s_nop 0
	v_addc_co_u32_e64 v5, s[4:5], 0, v5, s[4:5]
	v_mad_u64_u32 v[20:21], s[4:5], v39, s62, v[14:15]
	v_mad_u64_u32 v[22:23], s[4:5], v39, s62, v[16:17]
	v_mad_u64_u32 v[34:35], s[4:5], v39, s62, v[12:13]
	v_fma_f32 v39, -v37, v50, 1.0
	v_fmac_f32_e32 v50, v39, v50
	v_mul_f32_e32 v39, v40, v50
	v_fma_f32 v51, -v37, v39, v40
	v_fmac_f32_e32 v39, v51, v50
	v_fma_f32 v37, -v37, v39, v40
	v_div_fmas_f32 v37, v37, v50, v39
	v_div_fixup_f32 v7, v37, v7, 1.0
	v_mul_f32_e32 v25, v25, v7
	v_mul_f32_e32 v37, v41, v7
	v_mul_f32_e32 v39, v57, v7
	v_mul_f32_e32 v7, v73, v7
	v_add_u32_e32 v19, s30, v19
	v_add_u32_e32 v21, s30, v21
	v_add_u32_e32 v23, s30, v23
	v_add_u32_e32 v35, s30, v35
	v_or_b32_e32 v51, 17, v82
	s_waitcnt lgkmcnt(0)
	v_lshlrev_b32_e32 v2, 16, v2
	s_waitcnt lgkmcnt(0)
	v_lshlrev_b32_e32 v6, 16, v6
	s_waitcnt lgkmcnt(0)
	v_lshlrev_b32_e32 v24, 16, v24
	s_waitcnt lgkmcnt(0)
	v_lshlrev_b32_e32 v36, 16, v36
	v_mul_f32_e32 v2, v25, v2
	v_mul_f32_e32 v6, v37, v6
	v_mul_f32_e32 v24, v39, v24
	v_mul_f32_e32 v7, v7, v36
	v_bfe_u32 v25, v2, 16, 1
	v_bfe_u32 v36, v6, 16, 1
	v_bfe_u32 v37, v24, 16, 1
	v_bfe_u32 v39, v7, 16, 1
	v_add3_u32 v2, v2, v25, s61
	v_add3_u32 v6, v6, v36, s61
	v_add3_u32 v24, v24, v37, s61
	v_add3_u32 v7, v7, v39, s61
	ds_write_b16_d16_hi v206, v2 offset:2816
	ds_write_b16_d16_hi v206, v6 offset:2880
	ds_write_b16_d16_hi v206, v24 offset:2944
	ds_write_b16_d16_hi v206, v7 offset:3008
	ds_read_u16 v2, v206 offset:4096
	s_nop 0
	ds_read_u16 v40, v206 offset:4160
	ds_read_u16 v41, v206 offset:4224
	ds_read_u16 v50, v206 offset:4288
	ds_read_b128 v[18:21], v101 offset:192
	ds_read_b128 v[4:7], v101 offset:224
	v_mad_u64_u32 v[22:23], s[4:5], v51, s59, v[8:9]
	v_mad_u64_u32 v[24:25], s[4:5], v38, s62, v[10:11]
	s_waitcnt lgkmcnt(1)
	v_div_scale_f32 v52, s[4:5], v18, v18, 1.0
	v_rcp_f32_e32 v54, v52
	v_div_scale_f32 v53, vcc, 1.0, v18, 1.0
	v_add_u32_e32 v23, s2, v23
	v_fma_f32 v55, -v52, v54, 1.0
	v_fmac_f32_e32 v54, v55, v54
	v_mul_f32_e32 v55, v53, v54
	v_fma_f32 v56, -v52, v55, v53
	v_fmac_f32_e32 v55, v56, v54
	v_fma_f32 v52, -v52, v55, v53
	v_div_fmas_f32 v52, v52, v54, v55
	v_div_fixup_f32 v18, v52, v18, 1.0
	v_mul_f32_e32 v26, v26, v18
	v_mul_f32_e32 v42, v42, v18
	v_mul_f32_e32 v52, v58, v18
	v_mul_f32_e32 v18, v74, v18
	v_add_co_u32_e64 v22, s[4:5], s60, v22
	v_add_u32_e32 v25, s30, v25
	s_nop 0
	v_addc_co_u32_e64 v23, s[4:5], 0, v23, s[4:5]
	v_mad_u64_u32 v[34:35], s[4:5], v38, s62, v[14:15]
	v_mad_u64_u32 v[36:37], s[4:5], v38, s62, v[16:17]
	v_mad_u64_u32 v[38:39], s[4:5], v38, s62, v[12:13]
	v_add_u32_e32 v35, s30, v35
	v_add_u32_e32 v37, s30, v37
	v_add_u32_e32 v39, s30, v39
	s_waitcnt lgkmcnt(0)
; DI float bf2f(unsigned short u) { return __uint_as_float((unsigned)u << 16); }
; DI unsigned f2bf(float f) { unsigned u = __float_as_uint(f); return (u + 0x7fffu + ((u >> 16) & 1u)) >> 16; }
; DI int crow(int i, int hh) { return (i & 3) + 8 * (i >> 2) + 4 * hh; }
; DI void cross_unit(Ctx A_, LAS unsigned char* lds, int kvb, int hc, size_t row0, int nrows, int wave, int lane) {
;     ...
; #pragma unroll
;         for (int nb = 0; nb < 4; ++nb)
; #pragma unroll
;             for (int i = 0; i < 16; ++i) {
;                 const int q = rg * 32 + crow(i, hh);
;                 if (q < nrows) { const size_t eo = (row0 + q) * PLD + hc * 256 + dvh * 128 + nb * 32 + r; Y_[(row0 + q) * YLD + C_YC + hc * 256 + dvh * 128 + nb * 32 + r] = (bf16)f2bf(o[nb][i] * rl[i] * bf2f(P[eo + C_ZC])); }
;             }
	v_lshlrev_b32_e32 v2, 16, v2
	s_waitcnt lgkmcnt(0)
	v_lshlrev_b32_e32 v40, 16, v40
	s_waitcnt lgkmcnt(0)
	v_lshlrev_b32_e32 v41, 16, v41
	s_waitcnt lgkmcnt(0)
	v_lshlrev_b32_e32 v50, 16, v50
	v_mul_f32_e32 v2, v26, v2
	v_mul_f32_e32 v26, v42, v40
	v_mul_f32_e32 v40, v52, v41
	v_mul_f32_e32 v18, v18, v50
	v_bfe_u32 v41, v2, 16, 1
	v_bfe_u32 v42, v26, 16, 1
	v_bfe_u32 v50, v40, 16, 1
	v_bfe_u32 v52, v18, 16, 1
	v_add3_u32 v2, v2, v41, s61
	v_add3_u32 v26, v26, v42, s61
	v_add3_u32 v40, v40, v50, s61
	v_add3_u32 v18, v18, v52, s61
	ds_write_b16_d16_hi v206, v2 offset:4096
	ds_write_b16_d16_hi v206, v26 offset:4160
	ds_write_b16_d16_hi v206, v40 offset:4224
	ds_write_b16_d16_hi v206, v18 offset:4288
	ds_read_u16 v2, v206 offset:4352
	s_nop 0
	ds_read_u16 v18, v206 offset:4416
	ds_read_u16 v26, v206 offset:4480
	ds_read_u16 v40, v206 offset:4544
	v_div_scale_f32 v42, s[4:5], v19, v19, 1.0
	v_rcp_f32_e32 v52, v42
	v_or_b32_e32 v41, 18, v82
	v_mad_u64_u32 v[22:23], s[4:5], v41, s59, v[8:9]
	v_mad_u64_u32 v[24:25], s[4:5], v51, s62, v[10:11]
	v_add_u32_e32 v23, s2, v23
	v_add_co_u32_e64 v22, s[4:5], s60, v22
	v_div_scale_f32 v50, vcc, 1.0, v19, 1.0
	s_nop 0
	v_addc_co_u32_e64 v23, s[4:5], 0, v23, s[4:5]
	v_mad_u64_u32 v[34:35], s[4:5], v51, s62, v[14:15]
	v_mad_u64_u32 v[36:37], s[4:5], v51, s62, v[16:17]
	v_mad_u64_u32 v[38:39], s[4:5], v51, s62, v[12:13]
	v_fma_f32 v51, -v42, v52, 1.0
	v_fmac_f32_e32 v52, v51, v52
	v_mul_f32_e32 v51, v50, v52
	v_fma_f32 v53, -v42, v51, v50
	v_fmac_f32_e32 v51, v53, v52
	v_fma_f32 v42, -v42, v51, v50
	v_div_fmas_f32 v42, v42, v52, v51
	v_div_fixup_f32 v19, v42, v19, 1.0
	v_mul_f32_e32 v27, v27, v19
	v_mul_f32_e32 v42, v43, v19
	v_mul_f32_e32 v43, v59, v19
	v_mul_f32_e32 v19, v75, v19
	v_add_u32_e32 v25, s30, v25
	v_add_u32_e32 v35, s30, v35
	v_add_u32_e32 v37, s30, v37
	v_add_u32_e32 v39, s30, v39
	s_waitcnt lgkmcnt(0)
	v_lshlrev_b32_e32 v2, 16, v2
	s_waitcnt lgkmcnt(0)
	v_lshlrev_b32_e32 v18, 16, v18
	s_waitcnt lgkmcnt(0)
	v_lshlrev_b32_e32 v26, 16, v26
	s_waitcnt lgkmcnt(0)
	v_lshlrev_b32_e32 v40, 16, v40
	v_mul_f32_e32 v2, v27, v2
	v_mul_f32_e32 v18, v42, v18
	v_mul_f32_e32 v26, v43, v26
	v_mul_f32_e32 v19, v19, v40
	v_bfe_u32 v27, v2, 16, 1
	v_bfe_u32 v40, v18, 16, 1
	v_bfe_u32 v42, v26, 16, 1
	v_bfe_u32 v43, v19, 16, 1
	v_add3_u32 v2, v2, v27, s61
	v_add3_u32 v18, v18, v40, s61
	v_add3_u32 v26, v26, v42, s61
	v_add3_u32 v19, v19, v43, s61
	ds_write_b16_d16_hi v206, v2 offset:4352
	ds_write_b16_d16_hi v206, v18 offset:4416
	ds_write_b16_d16_hi v206, v26 offset:4480
	ds_write_b16_d16_hi v206, v19 offset:4544
	ds_read_u16 v2, v206 offset:4608
	s_nop 0
	ds_read_u16 v36, v206 offset:4672
	ds_read_u16 v37, v206 offset:4736
	ds_read_u16 v38, v206 offset:4800
	v_div_scale_f32 v40, s[4:5], v20, v20, 1.0
	v_rcp_f32_e32 v43, v40
	v_or_b32_e32 v39, 19, v82
	v_mad_u64_u32 v[18:19], s[4:5], v39, s59, v[8:9]
	v_mad_u64_u32 v[22:23], s[4:5], v41, s62, v[10:11]
	v_add_u32_e32 v19, s2, v19
	v_add_co_u32_e64 v18, s[4:5], s60, v18
	v_div_scale_f32 v42, vcc, 1.0, v20, 1.0
	s_nop 0
	v_addc_co_u32_e64 v19, s[4:5], 0, v19, s[4:5]
	v_mad_u64_u32 v[24:25], s[4:5], v41, s62, v[14:15]
	v_mad_u64_u32 v[26:27], s[4:5], v41, s62, v[16:17]
	v_mad_u64_u32 v[34:35], s[4:5], v41, s62, v[12:13]
	v_fma_f32 v41, -v40, v43, 1.0
	v_fmac_f32_e32 v43, v41, v43
	v_mul_f32_e32 v41, v42, v43
	v_fma_f32 v50, -v40, v41, v42
	v_fmac_f32_e32 v41, v50, v43
	v_fma_f32 v40, -v40, v41, v42
	v_div_fmas_f32 v40, v40, v43, v41
	v_div_fixup_f32 v20, v40, v20, 1.0
	v_mul_f32_e32 v28, v28, v20
	v_mul_f32_e32 v40, v44, v20
	v_mul_f32_e32 v41, v60, v20
	v_mul_f32_e32 v20, v76, v20
	v_add_u32_e32 v23, s30, v23
	v_add_u32_e32 v25, s30, v25
	v_add_u32_e32 v27, s30, v27
	v_add_u32_e32 v35, s30, v35
	s_waitcnt lgkmcnt(0)
	v_lshlrev_b32_e32 v2, 16, v2
	s_waitcnt lgkmcnt(0)
	v_lshlrev_b32_e32 v36, 16, v36
	s_waitcnt lgkmcnt(0)
	v_lshlrev_b32_e32 v37, 16, v37
	s_waitcnt lgkmcnt(0)
	v_lshlrev_b32_e32 v38, 16, v38
	v_mul_f32_e32 v2, v28, v2
	v_mul_f32_e32 v28, v40, v36
	v_mul_f32_e32 v36, v41, v37
	v_mul_f32_e32 v20, v20, v38
	v_bfe_u32 v37, v2, 16, 1
	v_bfe_u32 v38, v28, 16, 1
	v_bfe_u32 v40, v36, 16, 1
	v_bfe_u32 v41, v20, 16, 1
	v_add3_u32 v2, v2, v37, s61
	v_add3_u32 v28, v28, v38, s61
	v_add3_u32 v36, v36, v40, s61
	v_add3_u32 v20, v20, v41, s61
	ds_write_b16_d16_hi v206, v2 offset:4608
	ds_write_b16_d16_hi v206, v28 offset:4672
	ds_write_b16_d16_hi v206, v36 offset:4736
	ds_write_b16_d16_hi v206, v20 offset:4800
	ds_read_u16 v2, v206 offset:4864
	s_nop 0
	ds_read_u16 v20, v206 offset:4928
	ds_read_u16 v28, v206 offset:4992
	ds_read_u16 v36, v206 offset:5056
	v_div_scale_f32 v38, s[4:5], v21, v21, 1.0
	v_rcp_f32_e32 v41, v38
	v_or_b32_e32 v37, 24, v82
	v_mad_u64_u32 v[18:19], s[4:5], v37, s59, v[8:9]
	v_mad_u64_u32 v[22:23], s[4:5], v39, s62, v[10:11]
	v_add_u32_e32 v19, s2, v19
	v_add_co_u32_e64 v18, s[4:5], s60, v18
	v_div_scale_f32 v40, vcc, 1.0, v21, 1.0
	s_nop 0
	v_addc_co_u32_e64 v19, s[4:5], 0, v19, s[4:5]
	v_mad_u64_u32 v[24:25], s[4:5], v39, s62, v[14:15]
	v_mad_u64_u32 v[26:27], s[4:5], v39, s62, v[16:17]
	v_mad_u64_u32 v[34:35], s[4:5], v39, s62, v[12:13]
	v_fma_f32 v39, -v38, v41, 1.0
	v_fmac_f32_e32 v41, v39, v41
	v_mul_f32_e32 v39, v40, v41
	v_fma_f32 v42, -v38, v39, v40
	v_fmac_f32_e32 v39, v42, v41
	v_fma_f32 v38, -v38, v39, v40
	v_div_fmas_f32 v38, v38, v41, v39
	v_div_fixup_f32 v21, v38, v21, 1.0
	v_mul_f32_e32 v29, v29, v21
	v_mul_f32_e32 v38, v45, v21
	v_mul_f32_e32 v39, v61, v21
	v_mul_f32_e32 v21, v77, v21
	v_add_u32_e32 v23, s30, v23
	v_add_u32_e32 v25, s30, v25
	v_add_u32_e32 v27, s30, v27
	v_add_u32_e32 v35, s30, v35
	s_waitcnt lgkmcnt(0)
; DI float bf2f(unsigned short u) { return __uint_as_float((unsigned)u << 16); }
; DI unsigned f2bf(float f) { unsigned u = __float_as_uint(f); return (u + 0x7fffu + ((u >> 16) & 1u)) >> 16; }
; DI int crow(int i, int hh) { return (i & 3) + 8 * (i >> 2) + 4 * hh; }
; DI void cross_unit(Ctx A_, LAS unsigned char* lds, int kvb, int hc, size_t row0, int nrows, int wave, int lane) {
;     ...
; #pragma unroll
;         for (int nb = 0; nb < 4; ++nb)
; #pragma unroll
;             for (int i = 0; i < 16; ++i) {
;                 const int q = rg * 32 + crow(i, hh);
;                 if (q < nrows) { const size_t eo = (row0 + q) * PLD + hc * 256 + dvh * 128 + nb * 32 + r; Y_[(row0 + q) * YLD + C_YC + hc * 256 + dvh * 128 + nb * 32 + r] = (bf16)f2bf(o[nb][i] * rl[i] * bf2f(P[eo + C_ZC])); }
;             }
	v_lshlrev_b32_e32 v2, 16, v2
	s_waitcnt lgkmcnt(0)
	v_lshlrev_b32_e32 v20, 16, v20
	s_waitcnt lgkmcnt(0)
	v_lshlrev_b32_e32 v28, 16, v28
	s_waitcnt lgkmcnt(0)
	v_lshlrev_b32_e32 v36, 16, v36
	v_mul_f32_e32 v2, v29, v2
	v_mul_f32_e32 v20, v38, v20
	v_mul_f32_e32 v28, v39, v28
	v_mul_f32_e32 v21, v21, v36
	v_bfe_u32 v29, v2, 16, 1
	v_bfe_u32 v36, v20, 16, 1
	v_bfe_u32 v38, v28, 16, 1
	v_bfe_u32 v39, v21, 16, 1
	v_add3_u32 v2, v2, v29, s61
	v_add3_u32 v20, v20, v36, s61
	v_add3_u32 v28, v28, v38, s61
	v_add3_u32 v21, v21, v39, s61
	ds_write_b16_d16_hi v206, v2 offset:4864
	ds_write_b16_d16_hi v206, v20 offset:4928
	ds_write_b16_d16_hi v206, v28 offset:4992
	ds_write_b16_d16_hi v206, v21 offset:5056
	ds_read_u16 v2, v206 offset:6144
	s_nop 0
	ds_read_u16 v28, v206 offset:6208
	ds_read_u16 v29, v206 offset:6272
	ds_read_u16 v34, v206 offset:6336
	s_waitcnt lgkmcnt(0)
	v_div_scale_f32 v36, s[4:5], v4, v4, 1.0
	v_rcp_f32_e32 v39, v36
	v_or_b32_e32 v35, 25, v82
	v_mad_u64_u32 v[18:19], s[4:5], v35, s59, v[8:9]
	v_mad_u64_u32 v[20:21], s[4:5], v37, s62, v[10:11]
	v_add_u32_e32 v19, s2, v19
	v_add_co_u32_e64 v18, s[4:5], s60, v18
	v_div_scale_f32 v38, vcc, 1.0, v4, 1.0
	s_nop 0
	v_addc_co_u32_e64 v19, s[4:5], 0, v19, s[4:5]
	v_mad_u64_u32 v[22:23], s[4:5], v37, s62, v[14:15]
	v_mad_u64_u32 v[24:25], s[4:5], v37, s62, v[16:17]
	v_mad_u64_u32 v[26:27], s[4:5], v37, s62, v[12:13]
	v_fma_f32 v37, -v36, v39, 1.0
	v_fmac_f32_e32 v39, v37, v39
	v_mul_f32_e32 v37, v38, v39
	v_fma_f32 v40, -v36, v37, v38
	v_fmac_f32_e32 v37, v40, v39
	v_fma_f32 v36, -v36, v37, v38
	v_div_fmas_f32 v36, v36, v39, v37
	v_div_fixup_f32 v4, v36, v4, 1.0
	v_mul_f32_e32 v30, v30, v4
	v_mul_f32_e32 v36, v46, v4
	v_mul_f32_e32 v37, v62, v4
	v_mul_f32_e32 v4, v78, v4
	v_add_u32_e32 v21, s30, v21
	v_add_u32_e32 v23, s30, v23
	v_add_u32_e32 v25, s30, v25
	v_add_u32_e32 v27, s30, v27
	s_waitcnt lgkmcnt(0)
	v_lshlrev_b32_e32 v2, 16, v2
	s_waitcnt lgkmcnt(0)
	v_lshlrev_b32_e32 v28, 16, v28
	s_waitcnt lgkmcnt(0)
	v_lshlrev_b32_e32 v29, 16, v29
	s_waitcnt lgkmcnt(0)
	v_lshlrev_b32_e32 v34, 16, v34
	v_mul_f32_e32 v2, v30, v2
	v_mul_f32_e32 v28, v36, v28
	v_mul_f32_e32 v29, v37, v29
	v_mul_f32_e32 v4, v4, v34
	v_bfe_u32 v30, v2, 16, 1
	v_bfe_u32 v34, v28, 16, 1
	v_bfe_u32 v36, v29, 16, 1
	v_bfe_u32 v37, v4, 16, 1
	v_add3_u32 v2, v2, v30, s61
	v_add3_u32 v28, v28, v34, s61
	v_add3_u32 v29, v29, v36, s61
	v_add3_u32 v4, v4, v37, s61
	ds_write_b16_d16_hi v206, v2 offset:6144
	ds_write_b16_d16_hi v206, v28 offset:6208
	ds_write_b16_d16_hi v206, v29 offset:6272
	ds_write_b16_d16_hi v206, v4 offset:6336
	ds_read_u16 v2, v206 offset:6400
	s_nop 0
	ds_read_u16 v4, v206 offset:6464
	ds_read_u16 v28, v206 offset:6528
	ds_read_u16 v29, v206 offset:6592
	v_div_scale_f32 v34, s[4:5], v5, v5, 1.0
	v_rcp_f32_e32 v37, v34
	v_or_b32_e32 v30, 26, v82
	v_mad_u64_u32 v[18:19], s[4:5], v30, s59, v[8:9]
	v_mad_u64_u32 v[20:21], s[4:5], v35, s62, v[10:11]
	v_add_u32_e32 v19, s2, v19
	v_add_co_u32_e64 v18, s[4:5], s60, v18
	v_div_scale_f32 v36, vcc, 1.0, v5, 1.0
	s_nop 0
	v_addc_co_u32_e64 v19, s[4:5], 0, v19, s[4:5]
	v_mad_u64_u32 v[22:23], s[4:5], v35, s62, v[14:15]
	v_mad_u64_u32 v[24:25], s[4:5], v35, s62, v[16:17]
	v_mad_u64_u32 v[26:27], s[4:5], v35, s62, v[12:13]
	v_fma_f32 v35, -v34, v37, 1.0
	v_fmac_f32_e32 v37, v35, v37
	v_mul_f32_e32 v35, v36, v37
	v_fma_f32 v38, -v34, v35, v36
	v_fmac_f32_e32 v35, v38, v37
	v_fma_f32 v34, -v34, v35, v36
	v_div_fmas_f32 v34, v34, v37, v35
	v_div_fixup_f32 v5, v34, v5, 1.0
	v_mul_f32_e32 v31, v31, v5
	v_mul_f32_e32 v34, v47, v5
	v_mul_f32_e32 v35, v63, v5
	v_mul_f32_e32 v5, v79, v5
	v_add_u32_e32 v21, s30, v21
	v_add_u32_e32 v23, s30, v23
	v_add_u32_e32 v25, s30, v25
	v_add_u32_e32 v27, s30, v27
	s_waitcnt lgkmcnt(0)
	v_lshlrev_b32_e32 v2, 16, v2
	s_waitcnt lgkmcnt(0)
	v_lshlrev_b32_e32 v4, 16, v4
	s_waitcnt lgkmcnt(0)
	v_lshlrev_b32_e32 v28, 16, v28
	s_waitcnt lgkmcnt(0)
	v_lshlrev_b32_e32 v29, 16, v29
	v_mul_f32_e32 v2, v31, v2
	v_mul_f32_e32 v4, v34, v4
	v_mul_f32_e32 v28, v35, v28
	v_mul_f32_e32 v5, v5, v29
	v_bfe_u32 v29, v2, 16, 1
	v_bfe_u32 v31, v4, 16, 1
	v_bfe_u32 v34, v28, 16, 1
	v_bfe_u32 v35, v5, 16, 1
	v_add3_u32 v2, v2, v29, s61
	v_add3_u32 v4, v4, v31, s61
	v_add3_u32 v28, v28, v34, s61
	v_add3_u32 v5, v5, v35, s61
	ds_write_b16_d16_hi v206, v2 offset:6400
	ds_write_b16_d16_hi v206, v4 offset:6464
	ds_write_b16_d16_hi v206, v28 offset:6528
	ds_write_b16_d16_hi v206, v5 offset:6592
	ds_read_u16 v2, v206 offset:6656
	s_nop 0
	ds_read_u16 v24, v206 offset:6720
	ds_read_u16 v25, v206 offset:6784
	ds_read_u16 v26, v206 offset:6848
	v_div_scale_f32 v28, s[4:5], v6, v6, 1.0
	v_rcp_f32_e32 v31, v28
	v_or_b32_e32 v27, 27, v82
	v_mad_u64_u32 v[4:5], s[4:5], v27, s59, v[8:9]
	v_mad_u64_u32 v[8:9], s[4:5], v30, s62, v[10:11]
	v_add_u32_e32 v5, s2, v5
	v_add_co_u32_e64 v4, s[4:5], s60, v4
	v_div_scale_f32 v29, vcc, 1.0, v6, 1.0
	s_nop 0
	v_addc_co_u32_e64 v5, s[4:5], 0, v5, s[4:5]
	v_mad_u64_u32 v[18:19], s[4:5], v30, s62, v[14:15]
	v_mad_u64_u32 v[20:21], s[4:5], v30, s62, v[16:17]
	v_mad_u64_u32 v[22:23], s[4:5], v30, s62, v[12:13]
	v_fma_f32 v30, -v28, v31, 1.0
	v_fmac_f32_e32 v31, v30, v31
	v_mul_f32_e32 v30, v29, v31
	v_fma_f32 v34, -v28, v30, v29
	v_fmac_f32_e32 v30, v34, v31
	v_fma_f32 v28, -v28, v30, v29
	v_div_fmas_f32 v28, v28, v31, v30
	v_div_fixup_f32 v6, v28, v6, 1.0
	v_mul_f32_e32 v28, v32, v6
	v_mul_f32_e32 v29, v48, v6
	v_mul_f32_e32 v30, v64, v6
	v_mul_f32_e32 v6, v80, v6
	v_add_u32_e32 v9, s30, v9
	v_add_u32_e32 v19, s30, v19
	v_add_u32_e32 v21, s30, v21
	v_add_u32_e32 v23, s30, v23
	v_mad_u64_u32 v[12:13], s[4:5], v27, s62, v[12:13]
	v_add_u32_e32 v13, s30, v13
	s_waitcnt lgkmcnt(0)
; DI float bf2f(unsigned short u) { return __uint_as_float((unsigned)u << 16); }
; DI unsigned f2bf(float f) { unsigned u = __float_as_uint(f); return (u + 0x7fffu + ((u >> 16) & 1u)) >> 16; }
; DI int crow(int i, int hh) { return (i & 3) + 8 * (i >> 2) + 4 * hh; }
; DI void cross_unit(Ctx A_, LAS unsigned char* lds, int kvb, int hc, size_t row0, int nrows, int wave, int lane) {
;     ...
; #pragma unroll
;         for (int nb = 0; nb < 4; ++nb)
; #pragma unroll
;             for (int i = 0; i < 16; ++i) {
;                 const int q = rg * 32 + crow(i, hh);
;                 if (q < nrows) { const size_t eo = (row0 + q) * PLD + hc * 256 + dvh * 128 + nb * 32 + r; Y_[(row0 + q) * YLD + C_YC + hc * 256 + dvh * 128 + nb * 32 + r] = (bf16)f2bf(o[nb][i] * rl[i] * bf2f(P[eo + C_ZC])); }
;             }
;     }
;     asm volatile("s_waitcnt vmcnt(0) lgkmcnt(0)" ::: "memory"); __builtin_amdgcn_s_barrier(); asm volatile("" ::: "memory");
	v_lshlrev_b32_e32 v2, 16, v2
	s_waitcnt lgkmcnt(0)
	v_lshlrev_b32_e32 v24, 16, v24
	s_waitcnt lgkmcnt(0)
	v_lshlrev_b32_e32 v25, 16, v25
	s_waitcnt lgkmcnt(0)
	v_lshlrev_b32_e32 v26, 16, v26
	v_mul_f32_e32 v2, v28, v2
	v_mul_f32_e32 v24, v29, v24
	v_mul_f32_e32 v25, v30, v25
	v_mul_f32_e32 v6, v6, v26
	v_bfe_u32 v26, v2, 16, 1
	v_bfe_u32 v28, v24, 16, 1
	v_bfe_u32 v29, v25, 16, 1
	v_bfe_u32 v30, v6, 16, 1
	v_add3_u32 v2, v2, v26, s61
	v_add3_u32 v24, v24, v28, s61
	v_add3_u32 v25, v25, v29, s61
	v_add3_u32 v6, v6, v30, s61
	ds_write_b16_d16_hi v206, v2 offset:6656
	ds_write_b16_d16_hi v206, v24 offset:6720
	ds_write_b16_d16_hi v206, v25 offset:6784
	ds_write_b16_d16_hi v206, v6 offset:6848
	ds_read_u16 v2, v206 offset:6912
	s_nop 0
	ds_read_u16 v6, v206 offset:6976
	ds_read_u16 v18, v206 offset:7040
	ds_read_u16 v19, v206 offset:7104
	v_div_scale_f32 v20, s[4:5], v7, v7, 1.0
	v_rcp_f32_e32 v22, v20
	v_mad_u64_u32 v[8:9], s[4:5], v27, s62, v[14:15]
	v_div_scale_f32 v21, vcc, 1.0, v7, 1.0
	v_fma_f32 v14, -v20, v22, 1.0
	v_fmac_f32_e32 v22, v14, v22
	v_mul_f32_e32 v14, v21, v22
	v_fma_f32 v15, -v20, v14, v21
	v_fmac_f32_e32 v14, v15, v22
	v_fma_f32 v15, -v20, v14, v21
	v_div_fmas_f32 v14, v15, v22, v14
	v_div_fixup_f32 v7, v14, v7, 1.0
	v_mul_f32_e32 v14, v33, v7
	v_mad_u64_u32 v[4:5], s[4:5], v27, s62, v[10:11]
	v_mad_u64_u32 v[10:11], s[4:5], v27, s62, v[16:17]
	v_mul_f32_e32 v15, v49, v7
	v_mul_f32_e32 v16, v65, v7
	v_mul_f32_e32 v7, v81, v7
	v_add_u32_e32 v5, s30, v5
	v_add_u32_e32 v9, s30, v9
	v_add_u32_e32 v11, s30, v11
	s_waitcnt lgkmcnt(0)
	v_lshlrev_b32_e32 v2, 16, v2
	s_waitcnt lgkmcnt(0)
	v_lshlrev_b32_e32 v6, 16, v6
	s_waitcnt lgkmcnt(0)
	v_lshlrev_b32_e32 v17, 16, v18
	s_waitcnt lgkmcnt(0)
	v_lshlrev_b32_e32 v18, 16, v19
	v_mul_f32_e32 v2, v14, v2
	v_mul_f32_e32 v6, v15, v6
	v_mul_f32_e32 v14, v16, v17
	v_mul_f32_e32 v7, v7, v18
	v_bfe_u32 v15, v2, 16, 1
	v_bfe_u32 v16, v6, 16, 1
	v_bfe_u32 v17, v14, 16, 1
	v_bfe_u32 v18, v7, 16, 1
	v_add3_u32 v2, v2, v15, s61
	v_add3_u32 v6, v6, v16, s61
	v_add3_u32 v14, v14, v17, s61
	v_add3_u32 v7, v7, v18, s61
	ds_write_b16_d16_hi v206, v2 offset:6912
	ds_write_b16_d16_hi v206, v6 offset:6976
	ds_write_b16_d16_hi v206, v14 offset:7040
	ds_write_b16_d16_hi v206, v7 offset:7104
	s_waitcnt lgkmcnt(0)
	v_and_b32_e32 v207, 63, v0
	v_lshlrev_b32_e32 v208, 4, v207
	v_lshrrev_b32_e32 v210, 4, v207
	v_readfirstlane_b32 s98, v0
	s_lshr_b32 s98, s98, 6
	s_lshl_b32 s98, s98, 13
	s_add_u32 s98, s98, 0x10000
	v_add_u32_e32 v208, s98, v208
	v_mul_u32_u24_e32 v210, 0x1800, v210
	v_and_b32_e32 v207, 15, v207
	v_lshl_or_b32 v210, v207, 4, v210
	ds_read_b128 v[212:215], v208
	ds_read_b128 v[216:219], v208 offset:1024
	ds_read_b128 v[220:223], v208 offset:2048
	ds_read_b128 v[224:227], v208 offset:3072
	ds_read_b128 v[228:231], v208 offset:4096
	ds_read_b128 v[232:235], v208 offset:5120
	ds_read_b128 v[236:239], v208 offset:6144
	ds_read_b128 v[240:243], v208 offset:7168
	s_mul_hi_u32 s99, s101, 0x1800
	s_mul_i32 s98, s101, 0x1800
	v_readlane_b32 vcc_lo, v254, 62
	v_readlane_b32 vcc_hi, v254, 63
	s_add_u32 s98, s98, vcc_lo
	s_addc_u32 s99, s99, vcc_hi
	s_add_u32 s98, s98, 0x64900000
	s_addc_u32 s99, s99, 0
	s_sub_u32 s100, s100, 0x4000
	s_add_u32 s98, s98, s100
	s_addc_u32 s99, s99, 0
	s_waitcnt lgkmcnt(7)
	global_store_dwordx4 v210, v[212:215], s[98:99]
	s_add_u32 s98, s98, 0x6000
	s_addc_u32 s99, s99, 0
	s_waitcnt lgkmcnt(6)
	global_store_dwordx4 v210, v[216:219], s[98:99]
	s_add_u32 s98, s98, 0x6000
	s_addc_u32 s99, s99, 0
	s_waitcnt lgkmcnt(5)
	global_store_dwordx4 v210, v[220:223], s[98:99]
	s_add_u32 s98, s98, 0x6000
	s_addc_u32 s99, s99, 0
	s_waitcnt lgkmcnt(4)
	global_store_dwordx4 v210, v[224:227], s[98:99]
	s_add_u32 s98, s98, 0x6000
	s_addc_u32 s99, s99, 0
	s_waitcnt lgkmcnt(3)
	global_store_dwordx4 v210, v[228:231], s[98:99]
	s_add_u32 s98, s98, 0x6000
	s_addc_u32 s99, s99, 0
	s_waitcnt lgkmcnt(2)
	global_store_dwordx4 v210, v[232:235], s[98:99]
	s_add_u32 s98, s98, 0x6000
	s_addc_u32 s99, s99, 0
	s_waitcnt lgkmcnt(1)
	global_store_dwordx4 v210, v[236:239], s[98:99]
	s_add_u32 s98, s98, 0x6000
	s_addc_u32 s99, s99, 0
	s_waitcnt lgkmcnt(0)
	global_store_dwordx4 v210, v[240:243], s[98:99]
	s_waitcnt vmcnt(0) lgkmcnt(0)
	s_barrier

; DI int tid_now() { int t; asm volatile("v_mov_b32 %0, %1" : "=v"(t) : "v"((int)threadIdx.x)); return t; }
; #define Q_NEXT(k, id) do { if (tid == 0) qw[qit & 1] = __hip_atomic_fetch_add(qctr + 64 * (k), 1u, __ATOMIC_RELAXED, __HIP_MEMORY_SCOPE_AGENT); __syncthreads(); \
;         id = __builtin_amdgcn_readfirstlane((int)qw[qit & 1]); ++qit; } while (0)
; __global__ void __launch_bounds__(512, 2) fwd(Args args) {
;     ...
; #pragma unroll 1
;         for (;;) { int id; Q_NEXT(3, id); if (id >= 1152) break; const int lane = tid_now() & 63;
.LBB0_900:
	s_and_b32 s2, s36, 1
	s_and_saveexec_b64 s[4:5], s[82:83]
	s_cbranch_execz .LBB0_904
	s_mov_b64 s[34:35], exec
	v_mbcnt_lo_u32_b32 v2, s34, 0
	v_mbcnt_hi_u32_b32 v2, s35, v2
	v_cmp_eq_u32_e32 vcc, 0, v2
	s_and_saveexec_b64 s[30:31], vcc
	s_cbranch_execz .LBB0_903
	v_mov_b32_e32 v4, v205
	v_mov_b32_e32 v205, 1
	s_nop 0
	global_atomic_add v205, v3, v205, s[0:1] sc0

; DI float bf2f(unsigned short u) { return __uint_as_float((unsigned)u << 16); }
; DI unsigned f2bf(float f) { unsigned u = __float_as_uint(f); return (u + 0x7fffu + ((u >> 16) & 1u)) >> 16; }
; DI int crow(int i, int hh) { return (i & 3) + 8 * (i >> 2) + 4 * hh; }
; DI void cross_unit(Ctx A_, LAS unsigned char* lds, int kvb, int hc, size_t row0, int nrows, int wave, int lane) {
;     ...
;             for (int i = 0; i < 16; ++i) {
;                 const int q = rg * 32 + crow(i, hh);
;                 if (q < nrows) { const size_t eo = (row0 + q) * PLD + hc * 256 + dvh * 128 + nb * 32 + r; Y_[(row0 + q) * YLD + C_YC + hc * 256 + dvh * 128 + nb * 32 + r] = (bf16)f2bf(o[nb][i] * rl[i] * bf2f(P[eo + C_ZC])); }
.LctC_s:
	v_readfirstlane_b32 s34, v0
	s_lshr_b32 s34, s34, 6
	s_and_b32 s63, s34, 3
	s_lshl_b32 s63, s63, 5
	s_add_i32 s98, s98, s63
	s_lshr_b32 s63, s34, 2
	s_lshl_b32 s63, s63, 8
	s_lshl_b32 s100, s100, 9
	s_add_i32 s100, s100, s63
	s_add_i32 s100, s100, 0x5000
	s_mov_b32 s101, s98
	s_mul_hi_u32 s99, s98, 0x5800
	s_mul_i32 s98, s98, 0x5800
	v_readlane_b32 s63, v255, 9
	v_and_b32_e32 v206, 63, v0
	v_lshrrev_b32_e32 v207, 4, v206
	s_add_u32 s98, s98, s63
	v_readlane_b32 s63, v255, 10
	s_addc_u32 s99, s99, s63
	s_add_u32 s98, s98, s100
	s_addc_u32 s99, s99, 0
	v_mul_u32_u24_e32 v207, 0x5800, v207
	v_and_b32_e32 v206, 15, v206
	v_lshl_or_b32 v206, v206, 4, v207
	s_lshl_b32 s34, s34, 13
	s_add_i32 s34, s34, 0x10000
	s_mov_b32 m0, s34
	s_nop 0
	global_load_lds_dwordx4 v206, s[98:99]
	s_add_u32 s98, s98, 0x16000
	s_addc_u32 s99, s99, 0
	s_add_i32 s34, s34, 0x400
	s_mov_b32 m0, s34
	s_nop 0
	global_load_lds_dwordx4 v206, s[98:99]
	s_add_u32 s98, s98, 0x16000
	s_addc_u32 s99, s99, 0
	s_add_i32 s34, s34, 0x400
	s_mov_b32 m0, s34
	s_nop 0
	global_load_lds_dwordx4 v206, s[98:99]
	s_add_u32 s98, s98, 0x16000
	s_addc_u32 s99, s99, 0
	s_add_i32 s34, s34, 0x400
	s_mov_b32 m0, s34
	s_nop 0
	global_load_lds_dwordx4 v206, s[98:99]
	s_add_u32 s98, s98, 0x16000
	s_addc_u32 s99, s99, 0
	s_add_i32 s34, s34, 0x400
	s_mov_b32 m0, s34
	s_nop 0
	global_load_lds_dwordx4 v206, s[98:99]
	s_add_u32 s98, s98, 0x16000
	s_addc_u32 s99, s99, 0
	s_add_i32 s34, s34, 0x400
	s_mov_b32 m0, s34
	s_nop 0
	global_load_lds_dwordx4 v206, s[98:99]
	s_add_u32 s98, s98, 0x16000
	s_addc_u32 s99, s99, 0
	s_add_i32 s34, s34, 0x400
	s_mov_b32 m0, s34
	s_nop 0
	global_load_lds_dwordx4 v206, s[98:99]
	s_add_u32 s98, s98, 0x16000
	s_addc_u32 s99, s99, 0
	s_add_i32 s34, s34, 0x400
	s_mov_b32 m0, s34
	s_nop 0
	global_load_lds_dwordx4 v206, s[98:99]
